# folded redundant (0 + e0) first adds of the softmax row-sum chains in global and diff attention loops; on top of g6
# speedup vs baseline: 1.0063x; 1.0063x over previous
; DI float fexp2(float x) { return __builtin_amdgcn_exp2f(x); }
; DI void attn_core2(const u16* __restrict__ P, size_t tokbase, int kcol, int vcol, int n1, int n2, int xs0, bool win, int tq0,
;                    float m0, float l0, const bf16x8 (&qreg)[2][4], f32x16 (&o)[2][2], float (&lsum)[2], char* lds) {
;     ...
;         float la = 0.f;
;         if (mz[qs]) {
; #pragma unroll
;           for (int reg = 0; reg < 16; ++reg) { const float e = fexp2(pt[qs][reg]); pt[qs][reg] = e; la += e; }
;         } else {
; #pragma unroll
;           for (int reg = 0; reg < 16; ++reg) { const float e = fexp2(pt[qs][reg] - m[qs]); pt[qs][reg] = e; la += e; }
;         }
;         l[qs] += la;
.LBB0_130:
	s_andn2_b64 vcc, exec, s[40:41]
	s_mov_b64 s[0:1], -1
	s_cbranch_vccz .LBB0_132
	v_sub_f32_e32 v0, v32, v64
	v_exp_f32_e32 v0, v0
	v_sub_f32_e32 v1, v33, v64
	v_exp_f32_e32 v1, v1
	v_sub_f32_e32 v2, v34, v64
	v_exp_f32_e32 v2, v2
	v_add_f32_e32 v3, v1, v0
	v_sub_f32_e32 v4, v36, v64
	v_add_f32_e32 v7, v2, v3
	v_sub_f32_e32 v3, v35, v64
	v_exp_f32_e32 v3, v3
	v_exp_f32_e32 v4, v4
	v_sub_f32_e32 v5, v37, v64
	v_exp_f32_e32 v5, v5
	v_sub_f32_e32 v6, v38, v64
	v_exp_f32_e32 v6, v6
	v_add_f32_e32 v7, v3, v7
	v_add_f32_e32 v7, v4, v7
	v_add_f32_e32 v7, v5, v7
	v_add_f32_e32 v11, v6, v7
	v_sub_f32_e32 v7, v39, v64
	v_exp_f32_e32 v7, v7
	v_sub_f32_e32 v8, v40, v64
	v_exp_f32_e32 v8, v8
	v_sub_f32_e32 v9, v41, v64
	v_exp_f32_e32 v9, v9
	v_sub_f32_e32 v10, v42, v64
	v_exp_f32_e32 v10, v10
	v_add_f32_e32 v11, v7, v11
	v_add_f32_e32 v11, v8, v11
	v_add_f32_e32 v11, v9, v11
	v_add_f32_e32 v15, v10, v11
	v_sub_f32_e32 v11, v43, v64
	v_exp_f32_e32 v11, v11
	v_sub_f32_e32 v12, v44, v64
	v_exp_f32_e32 v12, v12
	v_sub_f32_e32 v13, v45, v64
	v_exp_f32_e32 v13, v13
	v_sub_f32_e32 v14, v46, v64
	v_exp_f32_e32 v14, v14
	v_add_f32_e32 v15, v11, v15
	v_add_f32_e32 v15, v12, v15
	v_add_f32_e32 v15, v13, v15
	v_add_f32_e32 v222, v14, v15
	v_sub_f32_e32 v15, v47, v64
	s_mov_b64 s[0:1], 0
.LBB0_132:
	s_andn2_b64 vcc, exec, s[0:1]
	s_cbranch_vccnz .LBB0_134
	v_exp_f32_e32 v0, v32
	v_exp_f32_e32 v1, v33
	v_exp_f32_e32 v2, v34
	v_exp_f32_e32 v3, v35
	v_add_f32_e32 v4, v1, v0
	v_add_f32_e32 v7, v2, v4
	v_exp_f32_e32 v4, v36
	v_exp_f32_e32 v5, v37
	v_exp_f32_e32 v6, v38
	v_add_f32_e32 v7, v3, v7
	v_add_f32_e32 v7, v4, v7
	v_add_f32_e32 v7, v5, v7
	v_add_f32_e32 v11, v6, v7
	v_exp_f32_e32 v7, v39
	v_exp_f32_e32 v8, v40
	v_exp_f32_e32 v9, v41
	v_exp_f32_e32 v10, v42
	v_add_f32_e32 v11, v7, v11
	v_add_f32_e32 v11, v8, v11
	v_add_f32_e32 v11, v9, v11
	v_add_f32_e32 v15, v10, v11
	v_exp_f32_e32 v11, v43
	v_exp_f32_e32 v12, v44
	v_exp_f32_e32 v13, v45
	v_exp_f32_e32 v14, v46
	v_add_f32_e32 v15, v11, v15
	v_add_f32_e32 v15, v12, v15
	v_add_f32_e32 v15, v13, v15
	v_add_f32_e32 v222, v14, v15
	v_mov_b32_e32 v15, v47

; DI float fexp2(float x) { return __builtin_amdgcn_exp2f(x); }
; DI void attn_core2(const u16* __restrict__ P, size_t tokbase, int kcol, int vcol, int n1, int n2, int xs0, bool win, int tq0,
;                    float m0, float l0, const bf16x8 (&qreg)[2][4], f32x16 (&o)[2][2], float (&lsum)[2], char* lds) {
;     ...
;         float la = 0.f;
;         if (mz[qs]) {
; #pragma unroll
;           for (int reg = 0; reg < 16; ++reg) { const float e = fexp2(pt[qs][reg]); pt[qs][reg] = e; la += e; }
;         } else {
; #pragma unroll
;           for (int reg = 0; reg < 16; ++reg) { const float e = fexp2(pt[qs][reg] - m[qs]); pt[qs][reg] = e; la += e; }
;         }
;         l[qs] += la;
.LBB0_136:
	v_exp_f32_e32 v15, v15
	s_mov_b64 s[0:1], -1
	s_and_b64 vcc, exec, s[38:39]
	s_cbranch_vccnz .LBB0_138
	v_sub_f32_e32 v32, v16, v186
	v_exp_f32_e32 v206, v32
	v_mov_b64_e32 v[62:63], v[30:31]
	v_mov_b64_e32 v[48:49], v[16:17]
	v_sub_f32_e32 v48, v17, v186
	v_mov_b64_e32 v[50:51], v[18:19]
	v_exp_f32_e32 v49, v48
	v_sub_f32_e32 v48, v18, v186
	v_exp_f32_e32 v50, v48
	v_mov_b64_e32 v[54:55], v[22:23]
	v_add_f32_e32 v51, v49, v206
	v_mov_b64_e32 v[52:53], v[20:21]
	v_add_f32_e32 v55, v50, v51
	v_sub_f32_e32 v51, v19, v186
	v_exp_f32_e32 v51, v51
	v_sub_f32_e32 v52, v20, v186
	v_exp_f32_e32 v52, v52
	v_sub_f32_e32 v53, v21, v186
	v_exp_f32_e32 v53, v53
	v_sub_f32_e32 v54, v22, v186
	v_exp_f32_e32 v54, v54
	v_add_f32_e32 v55, v51, v55
	v_add_f32_e32 v55, v52, v55
	v_mov_b64_e32 v[58:59], v[26:27]
	v_add_f32_e32 v55, v53, v55
	v_mov_b64_e32 v[56:57], v[24:25]
	v_add_f32_e32 v59, v54, v55
	v_sub_f32_e32 v55, v23, v186
	v_exp_f32_e32 v55, v55
	v_sub_f32_e32 v56, v24, v186
	v_exp_f32_e32 v56, v56
	v_sub_f32_e32 v57, v25, v186
	v_exp_f32_e32 v57, v57
	v_sub_f32_e32 v58, v26, v186
	v_exp_f32_e32 v58, v58
	v_add_f32_e32 v59, v55, v59
	v_add_f32_e32 v59, v56, v59
	v_add_f32_e32 v59, v57, v59
	v_mov_b64_e32 v[60:61], v[28:29]
	v_add_f32_e32 v63, v58, v59
	v_sub_f32_e32 v59, v27, v186
	v_exp_f32_e32 v59, v59
	v_sub_f32_e32 v60, v28, v186
	v_exp_f32_e32 v60, v60
	v_sub_f32_e32 v61, v29, v186
	v_exp_f32_e32 v61, v61
	v_sub_f32_e32 v62, v30, v186
	v_exp_f32_e32 v62, v62
	v_add_f32_e32 v63, v59, v63
	v_add_f32_e32 v63, v60, v63
	v_add_f32_e32 v63, v61, v63
	v_mov_b32_e32 v48, v206
	v_add_f32_e32 v221, v62, v63
	v_sub_f32_e32 v223, v31, v186
	v_mov_b64_e32 v[16:17], v[48:49]
	v_mov_b64_e32 v[18:19], v[50:51]
	v_mov_b64_e32 v[20:21], v[52:53]
	v_mov_b64_e32 v[22:23], v[54:55]
	v_mov_b64_e32 v[24:25], v[56:57]
	v_mov_b64_e32 v[26:27], v[58:59]
	v_mov_b64_e32 v[28:29], v[60:61]
	v_mov_b64_e32 v[30:31], v[62:63]
	s_mov_b64 s[0:1], 0
.LBB0_138:
	s_andn2_b64 vcc, exec, s[0:1]
	s_cbranch_vccnz .LBB0_140
	v_exp_f32_e32 v16, v16
	v_exp_f32_e32 v17, v17
	v_exp_f32_e32 v18, v18
	v_exp_f32_e32 v19, v19
	v_exp_f32_e32 v20, v20
	v_add_f32_e32 v32, v17, v16
	v_exp_f32_e32 v21, v21
	v_add_f32_e32 v32, v18, v32
	v_exp_f32_e32 v22, v22
	v_add_f32_e32 v32, v19, v32
	v_exp_f32_e32 v23, v23
	v_add_f32_e32 v32, v20, v32
	v_exp_f32_e32 v24, v24
	v_add_f32_e32 v32, v21, v32
	v_exp_f32_e32 v25, v25
	v_add_f32_e32 v32, v22, v32
	v_exp_f32_e32 v26, v26
	v_add_f32_e32 v32, v23, v32
	v_exp_f32_e32 v27, v27
	v_add_f32_e32 v32, v24, v32
	v_exp_f32_e32 v28, v28
	v_add_f32_e32 v32, v25, v32
	v_exp_f32_e32 v29, v29
	v_add_f32_e32 v32, v26, v32
	v_exp_f32_e32 v30, v30
	v_add_f32_e32 v32, v27, v32
	v_add_f32_e32 v32, v28, v32
	v_add_f32_e32 v32, v29, v32
	v_add_f32_e32 v221, v30, v32
	v_mov_b32_e32 v223, v31

; DI float fexp2(float x) { return __builtin_amdgcn_exp2f(x); }
; DI void attn_core2(const u16* __restrict__ P, size_t tokbase, int kcol, int vcol, int n1, int n2, int xs0, bool win, int tq0,
;                    float m0, float l0, const bf16x8 (&qreg)[2][4], f32x16 (&o)[2][2], float (&lsum)[2], char* lds) {
;     ...
;         float la = 0.f;
;         if (mz[qs]) {
; #pragma unroll
;           for (int reg = 0; reg < 16; ++reg) { const float e = fexp2(pt[qs][reg]); pt[qs][reg] = e; la += e; }
;         } else {
; #pragma unroll
;           for (int reg = 0; reg < 16; ++reg) { const float e = fexp2(pt[qs][reg] - m[qs]); pt[qs][reg] = e; la += e; }
;         }
;         l[qs] += la;
.LBB0_142:
	s_mov_b64 s[0:1], -1
	s_and_b64 vcc, exec, s[40:41]
	s_cbranch_vccnz .LBB0_144
	v_sub_f32_e32 v0, v32, v64
	v_exp_f32_e32 v0, v0
	v_sub_f32_e32 v1, v33, v64
	v_exp_f32_e32 v1, v1
	v_sub_f32_e32 v2, v34, v64
	v_exp_f32_e32 v2, v2
	v_add_f32_e32 v3, v1, v0
	v_sub_f32_e32 v4, v36, v64
	v_add_f32_e32 v7, v2, v3
	v_sub_f32_e32 v3, v35, v64
	v_exp_f32_e32 v3, v3
	v_exp_f32_e32 v4, v4
	v_sub_f32_e32 v5, v37, v64
	v_exp_f32_e32 v5, v5
	v_sub_f32_e32 v6, v38, v64
	v_exp_f32_e32 v6, v6
	v_add_f32_e32 v7, v3, v7
	v_add_f32_e32 v7, v4, v7
	v_add_f32_e32 v7, v5, v7
	v_add_f32_e32 v11, v6, v7
	v_sub_f32_e32 v7, v39, v64
	v_exp_f32_e32 v7, v7
	v_sub_f32_e32 v8, v40, v64
	v_exp_f32_e32 v8, v8
	v_sub_f32_e32 v9, v41, v64
	v_exp_f32_e32 v9, v9
	v_sub_f32_e32 v10, v42, v64
	v_exp_f32_e32 v10, v10
	v_add_f32_e32 v11, v7, v11
	v_add_f32_e32 v11, v8, v11
	v_add_f32_e32 v11, v9, v11
	v_add_f32_e32 v48, v10, v11
	v_sub_f32_e32 v11, v43, v64
	v_exp_f32_e32 v11, v11
	v_sub_f32_e32 v12, v44, v64
	v_exp_f32_e32 v12, v12
	v_sub_f32_e32 v13, v45, v64
	v_exp_f32_e32 v13, v13
	v_sub_f32_e32 v14, v46, v64
	v_exp_f32_e32 v14, v14
	v_add_f32_e32 v48, v11, v48
	v_add_f32_e32 v48, v12, v48
	v_add_f32_e32 v48, v13, v48
	v_add_f32_e32 v223, v14, v48
	v_sub_f32_e32 v48, v47, v64
	s_mov_b64 s[0:1], 0
.LBB0_144:
	s_andn2_b64 vcc, exec, s[0:1]
	s_cbranch_vccnz .LBB0_146
	v_exp_f32_e32 v0, v32
	v_exp_f32_e32 v1, v33
	v_exp_f32_e32 v2, v34
	v_exp_f32_e32 v3, v35
	v_add_f32_e32 v4, v1, v0
	v_add_f32_e32 v7, v2, v4
	v_exp_f32_e32 v4, v36
	v_exp_f32_e32 v5, v37
	v_exp_f32_e32 v6, v38
	v_add_f32_e32 v7, v3, v7
	v_add_f32_e32 v7, v4, v7
	v_add_f32_e32 v7, v5, v7
	v_add_f32_e32 v11, v6, v7
	v_exp_f32_e32 v7, v39
	v_exp_f32_e32 v8, v40
	v_exp_f32_e32 v9, v41
	v_exp_f32_e32 v10, v42
	v_add_f32_e32 v11, v7, v11
	v_add_f32_e32 v11, v8, v11
	v_add_f32_e32 v11, v9, v11
	v_add_f32_e32 v32, v10, v11
	v_exp_f32_e32 v11, v43
	v_exp_f32_e32 v12, v44
	v_exp_f32_e32 v13, v45
	v_exp_f32_e32 v14, v46
	v_add_f32_e32 v32, v11, v32
	v_add_f32_e32 v32, v12, v32
	v_add_f32_e32 v32, v13, v32
	v_add_f32_e32 v223, v14, v32
	v_mov_b32_e32 v48, v47

; DI float fexp2(float x) { return __builtin_amdgcn_exp2f(x); }
; DI void attn_core2(const u16* __restrict__ P, size_t tokbase, int kcol, int vcol, int n1, int n2, int xs0, bool win, int tq0,
;                    float m0, float l0, const bf16x8 (&qreg)[2][4], f32x16 (&o)[2][2], float (&lsum)[2], char* lds) {
;     ...
;         float la = 0.f;
;         if (mz[qs]) {
; #pragma unroll
;           for (int reg = 0; reg < 16; ++reg) { const float e = fexp2(pt[qs][reg]); pt[qs][reg] = e; la += e; }
;         } else {
; #pragma unroll
;           for (int reg = 0; reg < 16; ++reg) { const float e = fexp2(pt[qs][reg] - m[qs]); pt[qs][reg] = e; la += e; }
;         }
;         l[qs] += la;
.LBB0_148:
	v_exp_f32_e32 v15, v48
	s_mov_b64 s[0:1], -1
	s_and_b64 vcc, exec, s[38:39]
	s_cbranch_vccnz .LBB0_150
	v_sub_f32_e32 v32, v16, v186
	v_exp_f32_e32 v206, v32
	v_mov_b64_e32 v[62:63], v[30:31]
	v_mov_b64_e32 v[48:49], v[16:17]
	v_sub_f32_e32 v48, v17, v186
	v_mov_b64_e32 v[50:51], v[18:19]
	v_exp_f32_e32 v49, v48
	v_sub_f32_e32 v48, v18, v186
	v_exp_f32_e32 v50, v48
	v_mov_b64_e32 v[54:55], v[22:23]
	v_add_f32_e32 v51, v49, v206
	v_mov_b64_e32 v[52:53], v[20:21]
	v_add_f32_e32 v55, v50, v51
	v_sub_f32_e32 v51, v19, v186
	v_exp_f32_e32 v51, v51
	v_sub_f32_e32 v52, v20, v186
	v_exp_f32_e32 v52, v52
	v_sub_f32_e32 v53, v21, v186
	v_exp_f32_e32 v53, v53
	v_sub_f32_e32 v54, v22, v186
	v_exp_f32_e32 v54, v54
	v_add_f32_e32 v55, v51, v55
	v_add_f32_e32 v55, v52, v55
	v_mov_b64_e32 v[58:59], v[26:27]
	v_add_f32_e32 v55, v53, v55
	v_mov_b64_e32 v[56:57], v[24:25]
	v_add_f32_e32 v59, v54, v55
	v_sub_f32_e32 v55, v23, v186
	v_exp_f32_e32 v55, v55
	v_sub_f32_e32 v56, v24, v186
	v_exp_f32_e32 v56, v56
	v_sub_f32_e32 v57, v25, v186
	v_exp_f32_e32 v57, v57
	v_sub_f32_e32 v58, v26, v186
	v_exp_f32_e32 v58, v58
	v_add_f32_e32 v59, v55, v59
	v_add_f32_e32 v59, v56, v59
	v_add_f32_e32 v59, v57, v59
	v_mov_b64_e32 v[60:61], v[28:29]
	v_add_f32_e32 v63, v58, v59
	v_sub_f32_e32 v59, v27, v186
	v_exp_f32_e32 v59, v59
	v_sub_f32_e32 v60, v28, v186
	v_exp_f32_e32 v60, v60
	v_sub_f32_e32 v61, v29, v186
	v_exp_f32_e32 v61, v61
	v_sub_f32_e32 v62, v30, v186
	v_exp_f32_e32 v62, v62
	v_add_f32_e32 v63, v59, v63
	v_add_f32_e32 v63, v60, v63
	v_add_f32_e32 v63, v61, v63
	v_mov_b32_e32 v48, v206
	v_add_f32_e32 v222, v62, v63
	v_sub_f32_e32 v219, v31, v186
	v_mov_b64_e32 v[16:17], v[48:49]
	v_mov_b64_e32 v[18:19], v[50:51]
	v_mov_b64_e32 v[20:21], v[52:53]
	v_mov_b64_e32 v[22:23], v[54:55]
	v_mov_b64_e32 v[24:25], v[56:57]
	v_mov_b64_e32 v[26:27], v[58:59]
	v_mov_b64_e32 v[28:29], v[60:61]
	v_mov_b64_e32 v[30:31], v[62:63]
	s_mov_b64 s[0:1], 0
.LBB0_150:
	s_andn2_b64 vcc, exec, s[0:1]
	s_cbranch_vccnz .LBB0_152
	v_exp_f32_e32 v16, v16
	v_exp_f32_e32 v17, v17
	v_exp_f32_e32 v18, v18
	v_exp_f32_e32 v19, v19
	v_exp_f32_e32 v20, v20
	v_add_f32_e32 v32, v17, v16
	v_exp_f32_e32 v21, v21
	v_add_f32_e32 v32, v18, v32
	v_exp_f32_e32 v22, v22
	v_add_f32_e32 v32, v19, v32
	v_exp_f32_e32 v23, v23
	v_add_f32_e32 v32, v20, v32
	v_exp_f32_e32 v24, v24
	v_add_f32_e32 v32, v21, v32
	v_exp_f32_e32 v25, v25
	v_add_f32_e32 v32, v22, v32
	v_exp_f32_e32 v26, v26
	v_add_f32_e32 v32, v23, v32
	v_exp_f32_e32 v27, v27
	v_add_f32_e32 v32, v24, v32
	v_exp_f32_e32 v28, v28
	v_add_f32_e32 v32, v25, v32
	v_exp_f32_e32 v29, v29
	v_add_f32_e32 v32, v26, v32
	v_exp_f32_e32 v30, v30
	v_add_f32_e32 v32, v27, v32
	v_add_f32_e32 v32, v28, v32
	v_add_f32_e32 v32, v29, v32
	v_add_f32_e32 v222, v30, v32
	v_mov_b32_e32 v219, v31

; DI float fexp2(float x) { return __builtin_amdgcn_exp2f(x); }
; DI void attn_core2(const u16* __restrict__ P, size_t tokbase, int kcol, int vcol, int n1, int n2, int xs0, bool win, int tq0,
;                    float m0, float l0, const bf16x8 (&qreg)[2][4], f32x16 (&o)[2][2], float (&lsum)[2], char* lds) {
;     ...
;         float la = 0.f;
;         if (mz[qs]) {
; #pragma unroll
;           for (int reg = 0; reg < 16; ++reg) { const float e = fexp2(pt[qs][reg]); pt[qs][reg] = e; la += e; }
;         } else {
; #pragma unroll
;           for (int reg = 0; reg < 16; ++reg) { const float e = fexp2(pt[qs][reg] - m[qs]); pt[qs][reg] = e; la += e; }
;         }
;         l[qs] += la;
.LBB0_156:
	s_andn2_b64 vcc, exec, s[40:41]
	s_mov_b64 s[0:1], -1
	s_cbranch_vccz .LBB0_158
	v_sub_f32_e32 v0, v32, v64
	v_exp_f32_e32 v0, v0
	v_sub_f32_e32 v1, v33, v64
	v_exp_f32_e32 v1, v1
	v_sub_f32_e32 v2, v34, v64
	v_exp_f32_e32 v2, v2
	v_add_f32_e32 v3, v1, v0
	v_sub_f32_e32 v4, v36, v64
	v_add_f32_e32 v7, v2, v3
	v_sub_f32_e32 v3, v35, v64
	v_exp_f32_e32 v3, v3
	v_exp_f32_e32 v4, v4
	v_sub_f32_e32 v5, v37, v64
	v_exp_f32_e32 v5, v5
	v_sub_f32_e32 v6, v38, v64
	v_exp_f32_e32 v6, v6
	v_add_f32_e32 v7, v3, v7
	v_add_f32_e32 v7, v4, v7
	v_add_f32_e32 v7, v5, v7
	v_add_f32_e32 v11, v6, v7
	v_sub_f32_e32 v7, v39, v64
	v_exp_f32_e32 v7, v7
	v_sub_f32_e32 v8, v40, v64
	v_exp_f32_e32 v8, v8
	v_sub_f32_e32 v9, v41, v64
	v_exp_f32_e32 v9, v9
	v_sub_f32_e32 v10, v42, v64
	v_exp_f32_e32 v10, v10
	v_add_f32_e32 v11, v7, v11
	v_add_f32_e32 v11, v8, v11
	v_add_f32_e32 v11, v9, v11
	v_add_f32_e32 v15, v10, v11
	v_sub_f32_e32 v11, v43, v64
	v_exp_f32_e32 v11, v11
	v_sub_f32_e32 v12, v44, v64
	v_exp_f32_e32 v12, v12
	v_sub_f32_e32 v13, v45, v64
	v_exp_f32_e32 v13, v13
	v_sub_f32_e32 v14, v46, v64
	v_exp_f32_e32 v14, v14
	v_add_f32_e32 v15, v11, v15
	v_add_f32_e32 v15, v12, v15
	v_add_f32_e32 v15, v13, v15
	v_add_f32_e32 v223, v14, v15
	v_sub_f32_e32 v15, v47, v64
	s_mov_b64 s[0:1], 0
.LBB0_158:
	s_andn2_b64 vcc, exec, s[0:1]
	s_cbranch_vccnz .LBB0_160
	v_exp_f32_e32 v0, v32
	v_exp_f32_e32 v1, v33
	v_exp_f32_e32 v2, v34
	v_exp_f32_e32 v3, v35
	v_add_f32_e32 v4, v1, v0
	v_add_f32_e32 v7, v2, v4
	v_exp_f32_e32 v4, v36
	v_exp_f32_e32 v5, v37
	v_exp_f32_e32 v6, v38
	v_add_f32_e32 v7, v3, v7
	v_add_f32_e32 v7, v4, v7
	v_add_f32_e32 v7, v5, v7
	v_add_f32_e32 v11, v6, v7
	v_exp_f32_e32 v7, v39
	v_exp_f32_e32 v8, v40
	v_exp_f32_e32 v9, v41
	v_exp_f32_e32 v10, v42
	v_add_f32_e32 v11, v7, v11
	v_add_f32_e32 v11, v8, v11
	v_add_f32_e32 v11, v9, v11
	v_add_f32_e32 v15, v10, v11
	v_exp_f32_e32 v11, v43
	v_exp_f32_e32 v12, v44
	v_exp_f32_e32 v13, v45
	v_exp_f32_e32 v14, v46
	v_add_f32_e32 v15, v11, v15
	v_add_f32_e32 v15, v12, v15
	v_add_f32_e32 v15, v13, v15
	v_add_f32_e32 v223, v14, v15
	v_mov_b32_e32 v15, v47

; DI float fexp2(float x) { return __builtin_amdgcn_exp2f(x); }
; DI void attn_core2(const u16* __restrict__ P, size_t tokbase, int kcol, int vcol, int n1, int n2, int xs0, bool win, int tq0,
;                    float m0, float l0, const bf16x8 (&qreg)[2][4], f32x16 (&o)[2][2], float (&lsum)[2], char* lds) {
;     ...
;         float la = 0.f;
;         if (mz[qs]) {
; #pragma unroll
;           for (int reg = 0; reg < 16; ++reg) { const float e = fexp2(pt[qs][reg]); pt[qs][reg] = e; la += e; }
;         } else {
; #pragma unroll
;           for (int reg = 0; reg < 16; ++reg) { const float e = fexp2(pt[qs][reg] - m[qs]); pt[qs][reg] = e; la += e; }
;         }
;         l[qs] += la;
.LBB0_162:
	v_exp_f32_e32 v15, v15
	s_mov_b64 s[0:1], -1
	s_and_b64 vcc, exec, s[38:39]
	s_cbranch_vccnz .LBB0_164
	v_sub_f32_e32 v32, v16, v186
	v_exp_f32_e32 v206, v32
	v_mov_b64_e32 v[62:63], v[30:31]
	v_mov_b64_e32 v[48:49], v[16:17]
	v_sub_f32_e32 v48, v17, v186
	v_mov_b64_e32 v[50:51], v[18:19]
	v_exp_f32_e32 v49, v48
	v_sub_f32_e32 v48, v18, v186
	v_exp_f32_e32 v50, v48
	v_mov_b64_e32 v[54:55], v[22:23]
	v_add_f32_e32 v51, v49, v206
	v_mov_b64_e32 v[52:53], v[20:21]
	v_add_f32_e32 v55, v50, v51
	v_sub_f32_e32 v51, v19, v186
	v_exp_f32_e32 v51, v51
	v_sub_f32_e32 v52, v20, v186
	v_exp_f32_e32 v52, v52
	v_sub_f32_e32 v53, v21, v186
	v_exp_f32_e32 v53, v53
	v_sub_f32_e32 v54, v22, v186
	v_exp_f32_e32 v54, v54
	v_add_f32_e32 v55, v51, v55
	v_add_f32_e32 v55, v52, v55
	v_mov_b64_e32 v[58:59], v[26:27]
	v_add_f32_e32 v55, v53, v55
	v_mov_b64_e32 v[56:57], v[24:25]
	v_add_f32_e32 v59, v54, v55
	v_sub_f32_e32 v55, v23, v186
	v_exp_f32_e32 v55, v55
	v_sub_f32_e32 v56, v24, v186
	v_exp_f32_e32 v56, v56
	v_sub_f32_e32 v57, v25, v186
	v_exp_f32_e32 v57, v57
	v_sub_f32_e32 v58, v26, v186
	v_exp_f32_e32 v58, v58
	v_add_f32_e32 v59, v55, v59
	v_add_f32_e32 v59, v56, v59
	v_add_f32_e32 v59, v57, v59
	v_mov_b64_e32 v[60:61], v[28:29]
	v_add_f32_e32 v63, v58, v59
	v_sub_f32_e32 v59, v27, v186
	v_exp_f32_e32 v59, v59
	v_sub_f32_e32 v60, v28, v186
	v_exp_f32_e32 v60, v60
	v_sub_f32_e32 v61, v29, v186
	v_exp_f32_e32 v61, v61
	v_sub_f32_e32 v62, v30, v186
	v_exp_f32_e32 v62, v62
	v_add_f32_e32 v63, v59, v63
	v_add_f32_e32 v63, v60, v63
	v_add_f32_e32 v63, v61, v63
	v_mov_b32_e32 v48, v206
	v_add_f32_e32 v222, v62, v63
	v_sub_f32_e32 v224, v31, v186
	v_mov_b64_e32 v[16:17], v[48:49]
	v_mov_b64_e32 v[18:19], v[50:51]
	v_mov_b64_e32 v[20:21], v[52:53]
	v_mov_b64_e32 v[22:23], v[54:55]
	v_mov_b64_e32 v[24:25], v[56:57]
	v_mov_b64_e32 v[26:27], v[58:59]
	v_mov_b64_e32 v[28:29], v[60:61]
	v_mov_b64_e32 v[30:31], v[62:63]
	s_mov_b64 s[0:1], 0
.LBB0_164:
	s_andn2_b64 vcc, exec, s[0:1]
	s_cbranch_vccnz .LBB0_166
	v_exp_f32_e32 v16, v16
	v_exp_f32_e32 v17, v17
	v_exp_f32_e32 v18, v18
	v_exp_f32_e32 v19, v19
	v_exp_f32_e32 v20, v20
	v_add_f32_e32 v32, v17, v16
	v_exp_f32_e32 v21, v21
	v_add_f32_e32 v32, v18, v32
	v_exp_f32_e32 v22, v22
	v_add_f32_e32 v32, v19, v32
	v_exp_f32_e32 v23, v23
	v_add_f32_e32 v32, v20, v32
	v_exp_f32_e32 v24, v24
	v_add_f32_e32 v32, v21, v32
	v_exp_f32_e32 v25, v25
	v_add_f32_e32 v32, v22, v32
	v_exp_f32_e32 v26, v26
	v_add_f32_e32 v32, v23, v32
	v_exp_f32_e32 v27, v27
	v_add_f32_e32 v32, v24, v32
	v_exp_f32_e32 v28, v28
	v_add_f32_e32 v32, v25, v32
	v_exp_f32_e32 v29, v29
	v_add_f32_e32 v32, v26, v32
	v_exp_f32_e32 v30, v30
	v_add_f32_e32 v32, v27, v32
	v_add_f32_e32 v32, v28, v32
	v_add_f32_e32 v32, v29, v32
	v_add_f32_e32 v222, v30, v32
	v_mov_b32_e32 v224, v31

; DI float fexp2(float x) { return __builtin_amdgcn_exp2f(x); }
; DI void attn_core2(const u16* __restrict__ P, size_t tokbase, int kcol, int vcol, int n1, int n2, int xs0, bool win, int tq0,
;                    float m0, float l0, const bf16x8 (&qreg)[2][4], f32x16 (&o)[2][2], float (&lsum)[2], char* lds) {
;     ...
;         float la = 0.f;
;         if (mz[qs]) {
; #pragma unroll
;           for (int reg = 0; reg < 16; ++reg) { const float e = fexp2(pt[qs][reg]); pt[qs][reg] = e; la += e; }
;         } else {
; #pragma unroll
;           for (int reg = 0; reg < 16; ++reg) { const float e = fexp2(pt[qs][reg] - m[qs]); pt[qs][reg] = e; la += e; }
;         }
;         l[qs] += la;
.LBB0_174:
	v_exp_f32_e32 v15, v48
	s_mov_b64 s[0:1], -1
	s_and_b64 vcc, exec, s[38:39]
	s_cbranch_vccnz .LBB0_176
	v_sub_f32_e32 v32, v16, v186
	v_exp_f32_e32 v206, v32
	v_mov_b64_e32 v[62:63], v[30:31]
	v_mov_b64_e32 v[48:49], v[16:17]
	v_sub_f32_e32 v48, v17, v186
	v_mov_b64_e32 v[50:51], v[18:19]
	v_exp_f32_e32 v49, v48
	v_sub_f32_e32 v48, v18, v186
	v_exp_f32_e32 v50, v48
	v_mov_b64_e32 v[54:55], v[22:23]
	v_add_f32_e32 v51, v49, v206
	v_mov_b64_e32 v[52:53], v[20:21]
	v_add_f32_e32 v55, v50, v51
	v_sub_f32_e32 v51, v19, v186
	v_exp_f32_e32 v51, v51
	v_sub_f32_e32 v52, v20, v186
	v_exp_f32_e32 v52, v52
	v_sub_f32_e32 v53, v21, v186
	v_exp_f32_e32 v53, v53
	v_sub_f32_e32 v54, v22, v186
	v_exp_f32_e32 v54, v54
	v_add_f32_e32 v55, v51, v55
	v_add_f32_e32 v55, v52, v55
	v_mov_b64_e32 v[58:59], v[26:27]
	v_add_f32_e32 v55, v53, v55
	v_mov_b64_e32 v[56:57], v[24:25]
	v_add_f32_e32 v59, v54, v55
	v_sub_f32_e32 v55, v23, v186
	v_exp_f32_e32 v55, v55
	v_sub_f32_e32 v56, v24, v186
	v_exp_f32_e32 v56, v56
	v_sub_f32_e32 v57, v25, v186
	v_exp_f32_e32 v57, v57
	v_sub_f32_e32 v58, v26, v186
	v_exp_f32_e32 v58, v58
	v_add_f32_e32 v59, v55, v59
	v_add_f32_e32 v59, v56, v59
	v_add_f32_e32 v59, v57, v59
	v_mov_b64_e32 v[60:61], v[28:29]
	v_add_f32_e32 v63, v58, v59
	v_sub_f32_e32 v59, v27, v186
	v_exp_f32_e32 v59, v59
	v_sub_f32_e32 v60, v28, v186
	v_exp_f32_e32 v60, v60
	v_sub_f32_e32 v61, v29, v186
	v_exp_f32_e32 v61, v61
	v_sub_f32_e32 v62, v30, v186
	v_exp_f32_e32 v62, v62
	v_add_f32_e32 v63, v59, v63
	v_add_f32_e32 v63, v60, v63
	v_add_f32_e32 v63, v61, v63
	v_mov_b32_e32 v48, v206
	v_add_f32_e32 v222, v62, v63
	v_sub_f32_e32 v224, v31, v186
	v_mov_b64_e32 v[16:17], v[48:49]
	v_mov_b64_e32 v[18:19], v[50:51]
	v_mov_b64_e32 v[20:21], v[52:53]
	v_mov_b64_e32 v[22:23], v[54:55]
	v_mov_b64_e32 v[24:25], v[56:57]
	v_mov_b64_e32 v[26:27], v[58:59]
	v_mov_b64_e32 v[28:29], v[60:61]
	v_mov_b64_e32 v[30:31], v[62:63]
	s_mov_b64 s[0:1], 0

; DI float fexp2(float x) { return __builtin_amdgcn_exp2f(x); }
; template <int DV>
; DI void attn_core(const u16* __restrict__ P, size_t tokbase, int kcol, int vcol, int n1, int n2, int xs0,
;                   bool win, int tq, float m0, float l0, f32x16 (&o)[DV / 32], float& lsum, char* lds) {
;     ...
;       float la = 0.f;
; #pragma unroll
;       for (int reg = 0; reg < 16; ++reg) { const float e = fexp2(pt[reg]); pt[reg] = e; la += e; }
;       l += la;
;     ...
;     for (int it = 0; it < ntiles; it += 2) {
;       if (it + 2 < ntiles) A_LOAD(kA, vA, it + 2);
;       compute(lds, it);
;       A_STORE(kB, vB, 1);
;       __syncthreads();
;       if (it + 3 < ntiles) A_LOAD(kB, vB, it + 3);
;       compute(lds + STAGE, it + 1);
;       if (it + 2 < ntiles) A_STORE(kA, vA, 0);
;       __syncthreads();
.LBB0_351:
	v_add_f32_e32 v64, v79, v64
	v_add_f32_e32 v64, v96, v64
	v_add_f32_e32 v64, v97, v64
	v_add_f32_e32 v64, v98, v64
	v_add_f32_e32 v64, v99, v64
	v_add_f32_e32 v64, v100, v64
	v_add_f32_e32 v64, v101, v64
	v_add_f32_e32 v64, v102, v64
	v_add_f32_e32 v64, v103, v64
	v_add_f32_e32 v64, v104, v64
	v_add_f32_e32 v64, v105, v64
	v_add_f32_e32 v64, v106, v64
	v_add_f32_e32 v64, v107, v64
	v_add_f32_e32 v64, v108, v64
	s_add_i32 s67, s67, 2
	v_add_f32_e32 v64, v109, v64
	s_add_u32 s2, s2, 0x172000
	v_add_f32_e32 v185, v78, v64
	s_addc_u32 s3, s3, 0
	s_andn2_b64 vcc, exec, s[0:1]
	s_waitcnt lgkmcnt(0)
	s_barrier
	s_cbranch_vccz .LBB0_372

; #define MFMA(a, b, c) __builtin_amdgcn_mfma_f32_32x32x16_bf16((a), (b), (c), 0, 0, 0)
; DI int crow(int reg, int h) { return (reg & 3) + 8 * (reg >> 2) + 4 * h; }
; DI s16x4 vtr(const char* p) { return __builtin_bit_cast(s16x4, __builtin_amdgcn_ds_read_tr16_b64_v4i16((__attribute__((address_space(3))) v4i16_t*)(lds_cptr)p)); }
; template <int DV>
; DI void attn_core(const u16* __restrict__ P, size_t tokbase, int kcol, int vcol, int n1, int n2, int xs0,
;                   bool win, int tq, float m0, float l0, f32x16 (&o)[DV / 32], float& lsum, char* lds) {
;     ...
;     for (int ks = 0; ks < 2; ++ks) {
;       f32x16 pt = negm;
; #pragma unroll
;       for (int s = 0; s < 4; ++s) {
;         const int ch = 2 * s + h, key = 32 * ks + r;
;         const bf16x8 kf = *(const bf16x8*)(base + ch * 1024 + ((key ^ ch) * 16));
;         const bf16x8 qf = qreg[s];
;         pt = MFMA(kf, qf, pt);
;       }
;       if (domask) {
; #pragma unroll
;         for (int reg = 0; reg < 16; ++reg) {
;           const int d = tq - (kt0 + 32 * ks + crow(reg, h));
;           if (d > 128 || d < -128) pt[reg] = -1e30f;
;         }
;       }
;       float mloc = mx2(pt[0], pt[1]);
; #pragma unroll
;       for (int reg = 2; reg < 16; reg += 2) mloc = mx2(mx2(mloc, pt[reg]), pt[reg + 1]);
;       mloc = hmax(mloc);
;       const bool first = autoinit && it == 0 && ks == 0;
;       if (first || __builtin_amdgcn_ballot_w64(mloc > THR) != 0) {
;         const float d = first ? mloc : fmaxf(mloc, 0.f);
;         const float alpha = fexp2(-d);
;         m += d; l *= alpha;
; #pragma unroll
;         for (int reg = 0; reg < 16; ++reg) { negm[reg] = -m; pt[reg] -= d; }
; #pragma unroll
;         for (int b = 0; b < DV / 32; ++b)
; #pragma unroll
;           for (int reg = 0; reg < 16; ++reg) o[b][reg] *= alpha;
;       }
;       float la = 0.f;
; #pragma unroll
;       for (int reg = 0; reg < 16; ++reg) { const float e = fexp2(pt[reg]); pt[reg] = e; la += e; }
;       l += la;
; #pragma unroll
;       for (int s2 = 0; s2 < 2; ++s2) {
;         const bf16x8 pb = pack8(pt, s2);
;         const int s16 = 2 * ks + s2;
; #pragma unroll
;         for (int b = 0; b < DV / 32; ++b) {
;           const char* va = base + KB + b * 4096 + s16 * 1024 + trofs;
;           const bf16x8 vf = cat8(vtr(va), vtr(va + 512));
;           o[b] = MFMA(vf, pb, o[b]);
;         }
;       }
.LBB0_359:
.LBB0_360:
	v_exp_f32_e32 v96, v96
	v_exp_f32_e32 v97, v97
	v_exp_f32_e32 v98, v98
	v_exp_f32_e32 v99, v99
	v_exp_f32_e32 v100, v100
	v_add_f32_e32 v186, v97, v96
	v_exp_f32_e32 v101, v101
	v_add_f32_e32 v186, v98, v186
	v_exp_f32_e32 v102, v102
	v_add_f32_e32 v186, v99, v186
	v_exp_f32_e32 v103, v103
	v_add_f32_e32 v186, v100, v186
	v_add_f32_e32 v186, v101, v186
	v_add_f32_e32 v186, v102, v186
	v_add_f32_e32 v186, v103, v186
	v_cvt_pk_bf16_f32 v96, v96, v97
	v_cvt_pk_bf16_f32 v97, v98, v99
	v_cvt_pk_bf16_f32 v98, v100, v101
	v_cvt_pk_bf16_f32 v99, v102, v103
	ds_read_b64_tr_b16 v[100:101], v159 offset:8192
	ds_read_b64_tr_b16 v[102:103], v159 offset:8704
	s_waitcnt lgkmcnt(0)
	v_mfma_f32_32x32x16_bf16 v[48:63], v[100:103], v[96:99], v[48:63]
	ds_read_b64_tr_b16 v[100:101], v159 offset:12288
	ds_read_b64_tr_b16 v[102:103], v159 offset:12800
	v_exp_f32_e32 v104, v104
	v_exp_f32_e32 v105, v105
	v_exp_f32_e32 v106, v106
	v_exp_f32_e32 v107, v107
	v_exp_f32_e32 v108, v108
	v_exp_f32_e32 v109, v109
	s_waitcnt lgkmcnt(0)
	v_mfma_f32_32x32x16_bf16 v[32:47], v[100:103], v[96:99], v[32:47]
	ds_read_b64_tr_b16 v[100:101], v159 offset:16384
	ds_read_b64_tr_b16 v[102:103], v159 offset:16896
	v_exp_f32_e32 v110, v110
	v_exp_f32_e32 v111, v111
	v_add_f32_e32 v186, v104, v186
	v_add_f32_e32 v186, v105, v186
	v_add_f32_e32 v186, v106, v186
	v_add_f32_e32 v186, v107, v186
	s_waitcnt lgkmcnt(0)
	v_mfma_f32_32x32x16_bf16 v[16:31], v[100:103], v[96:99], v[16:31]
	ds_read_b64_tr_b16 v[100:101], v159 offset:20480
	ds_read_b64_tr_b16 v[102:103], v159 offset:20992
	v_add_f32_e32 v186, v108, v186
	v_add_f32_e32 v186, v109, v186
	v_add_f32_e32 v186, v110, v186
	v_add_f32_e32 v186, v111, v186
	v_add_f32_e32 v186, v185, v186
	s_waitcnt lgkmcnt(0)
	v_mfma_f32_32x32x16_bf16 v[0:15], v[100:103], v[96:99], v[0:15]
	ds_read_b64_tr_b16 v[100:101], v159 offset:9216
	ds_read_b64_tr_b16 v[102:103], v159 offset:9728
	v_cvt_pk_bf16_f32 v96, v104, v105
	v_cvt_pk_bf16_f32 v97, v106, v107
	v_cvt_pk_bf16_f32 v98, v108, v109
	v_cvt_pk_bf16_f32 v99, v110, v111
	s_waitcnt lgkmcnt(0)
	s_nop 0
	v_mfma_f32_32x32x16_bf16 v[48:63], v[100:103], v[96:99], v[48:63]
	ds_read_b64_tr_b16 v[100:101], v159 offset:13312
	ds_read_b64_tr_b16 v[102:103], v159 offset:13824
	s_waitcnt lgkmcnt(0)
	v_mfma_f32_32x32x16_bf16 v[32:47], v[100:103], v[96:99], v[32:47]
	ds_read_b64_tr_b16 v[100:101], v159 offset:17408
	ds_read_b64_tr_b16 v[102:103], v159 offset:17920
	s_waitcnt lgkmcnt(0)
	v_mfma_f32_32x32x16_bf16 v[16:31], v[100:103], v[96:99], v[16:31]
	ds_read_b64_tr_b16 v[100:101], v159 offset:21504
	ds_read_b64_tr_b16 v[102:103], v159 offset:22016
	ds_read_b128 v[206:209], v161
	s_waitcnt lgkmcnt(1)
	v_mfma_f32_32x32x16_bf16 v[0:15], v[100:103], v[96:99], v[0:15]
	s_waitcnt lgkmcnt(0)
	v_mfma_f32_32x32x16_bf16 v[96:111], v[206:209], v[112:115], v[80:95]
	ds_read_b128 v[206:209], v162
	s_waitcnt lgkmcnt(0)
	v_mfma_f32_32x32x16_bf16 v[96:111], v[206:209], v[116:119], v[96:111]
	ds_read_b128 v[206:209], v163
	s_waitcnt lgkmcnt(0)
	v_mfma_f32_32x32x16_bf16 v[96:111], v[206:209], v[120:123], v[96:111]
	ds_read_b128 v[206:209], v164
	s_waitcnt lgkmcnt(0)
	v_mfma_f32_32x32x16_bf16 v[96:111], v[206:209], v[124:127], v[96:111]
	s_nop 11
	v_maximum3_f32 v185, v96, v97, v97
	v_maximum3_f32 v185, v185, v98, v99
	v_maximum3_f32 v185, v185, v100, v101
	v_maximum3_f32 v185, v185, v102, v103
	v_maximum3_f32 v185, v185, v104, v105
	v_maximum3_f32 v185, v185, v106, v107
	v_maximum3_f32 v185, v185, v108, v109
	v_maximum3_f32 v185, v185, v110, v111
	v_mov_b32_e32 v187, v185
	s_nop 1
	v_permlane32_swap_b32_e32 v185, v187
	v_maximum3_f32 v185, v185, v187, v187
	v_cmp_lt_f32_e32 vcc, s80, v185
	s_cbranch_vccz .LBB0_362
; DI float fexp2(float x) { return __builtin_amdgcn_exp2f(x); }
; template <int DV>
; DI void attn_core(const u16* __restrict__ P, size_t tokbase, int kcol, int vcol, int n1, int n2, int xs0,
;                   bool win, int tq, float m0, float l0, f32x16 (&o)[DV / 32], float& lsum, char* lds) {
;     ...
;       if (first || __builtin_amdgcn_ballot_w64(mloc > THR) != 0) {
;         const float d = first ? mloc : fmaxf(mloc, 0.f);
;         const float alpha = fexp2(-d);
;         m += d; l *= alpha;
; #pragma unroll
;         for (int reg = 0; reg < 16; ++reg) { negm[reg] = -m; pt[reg] -= d; }
; #pragma unroll
;         for (int b = 0; b < DV / 32; ++b)
; #pragma unroll
;           for (int reg = 0; reg < 16; ++reg) o[b][reg] *= alpha;
;       }
	v_max_f32_e32 v64, v185, v185
	v_max_f32_e32 v64, 0, v64
	v_exp_f32_e64 v82, -v64
	v_add_f32_e32 v165, v165, v64
	v_xor_b32_e32 v80, 0x80000000, v165
	v_pk_add_f32 v[96:97], v[96:97], v[64:65] op_sel_hi:[1,0] neg_lo:[0,1] neg_hi:[0,1]
	v_mul_f32_e32 v186, v186, v82
	v_pk_add_f32 v[98:99], v[98:99], v[64:65] op_sel_hi:[1,0] neg_lo:[0,1] neg_hi:[0,1]
	v_pk_add_f32 v[100:101], v[100:101], v[64:65] op_sel_hi:[1,0] neg_lo:[0,1] neg_hi:[0,1]
	v_pk_add_f32 v[102:103], v[102:103], v[64:65] op_sel_hi:[1,0] neg_lo:[0,1] neg_hi:[0,1]
	v_pk_add_f32 v[104:105], v[104:105], v[64:65] op_sel_hi:[1,0] neg_lo:[0,1] neg_hi:[0,1]
	v_pk_add_f32 v[106:107], v[106:107], v[64:65] op_sel_hi:[1,0] neg_lo:[0,1] neg_hi:[0,1]
	v_pk_add_f32 v[108:109], v[108:109], v[64:65] op_sel_hi:[1,0] neg_lo:[0,1] neg_hi:[0,1]
	v_pk_add_f32 v[110:111], v[110:111], v[64:65] op_sel_hi:[1,0] neg_lo:[0,1] neg_hi:[0,1]
	v_pk_mul_f32 v[62:63], v[62:63], v[82:83] op_sel_hi:[1,0]
	v_pk_mul_f32 v[60:61], v[60:61], v[82:83] op_sel_hi:[1,0]
	v_pk_mul_f32 v[58:59], v[58:59], v[82:83] op_sel_hi:[1,0]
	v_pk_mul_f32 v[56:57], v[56:57], v[82:83] op_sel_hi:[1,0]
	v_pk_mul_f32 v[54:55], v[54:55], v[82:83] op_sel_hi:[1,0]
	v_pk_mul_f32 v[52:53], v[52:53], v[82:83] op_sel_hi:[1,0]
	v_pk_mul_f32 v[50:51], v[50:51], v[82:83] op_sel_hi:[1,0]
	v_pk_mul_f32 v[48:49], v[48:49], v[82:83] op_sel_hi:[1,0]
	v_pk_mul_f32 v[46:47], v[46:47], v[82:83] op_sel_hi:[1,0]
	v_pk_mul_f32 v[44:45], v[44:45], v[82:83] op_sel_hi:[1,0]
	v_pk_mul_f32 v[42:43], v[42:43], v[82:83] op_sel_hi:[1,0]
	v_pk_mul_f32 v[40:41], v[40:41], v[82:83] op_sel_hi:[1,0]
	v_pk_mul_f32 v[38:39], v[38:39], v[82:83] op_sel_hi:[1,0]
	v_pk_mul_f32 v[36:37], v[36:37], v[82:83] op_sel_hi:[1,0]
	v_pk_mul_f32 v[34:35], v[34:35], v[82:83] op_sel_hi:[1,0]
	v_pk_mul_f32 v[32:33], v[32:33], v[82:83] op_sel_hi:[1,0]
	v_pk_mul_f32 v[30:31], v[30:31], v[82:83] op_sel_hi:[1,0]
	v_pk_mul_f32 v[28:29], v[28:29], v[82:83] op_sel_hi:[1,0]
	v_pk_mul_f32 v[26:27], v[26:27], v[82:83] op_sel_hi:[1,0]
	v_pk_mul_f32 v[24:25], v[24:25], v[82:83] op_sel_hi:[1,0]
	v_pk_mul_f32 v[22:23], v[22:23], v[82:83] op_sel_hi:[1,0]
	v_pk_mul_f32 v[20:21], v[20:21], v[82:83] op_sel_hi:[1,0]
	v_pk_mul_f32 v[18:19], v[18:19], v[82:83] op_sel_hi:[1,0]
	v_pk_mul_f32 v[16:17], v[16:17], v[82:83] op_sel_hi:[1,0]
	v_pk_mul_f32 v[14:15], v[14:15], v[82:83] op_sel_hi:[1,0]
	v_pk_mul_f32 v[12:13], v[12:13], v[82:83] op_sel_hi:[1,0]
	v_pk_mul_f32 v[10:11], v[10:11], v[82:83] op_sel_hi:[1,0]
	v_pk_mul_f32 v[8:9], v[8:9], v[82:83] op_sel_hi:[1,0]
	v_pk_mul_f32 v[6:7], v[6:7], v[82:83] op_sel_hi:[1,0]
	v_pk_mul_f32 v[4:5], v[4:5], v[82:83] op_sel_hi:[1,0]
	v_pk_mul_f32 v[2:3], v[2:3], v[82:83] op_sel_hi:[1,0]
	v_pk_mul_f32 v[0:1], v[0:1], v[82:83] op_sel_hi:[1,0]
	v_mov_b32_e32 v81, v80
	v_mov_b32_e32 v82, v80
	v_mov_b32_e32 v83, v80
	v_mov_b32_e32 v84, v80
	v_mov_b32_e32 v85, v80
	v_mov_b32_e32 v86, v80
	v_mov_b32_e32 v87, v80
	v_mov_b32_e32 v88, v80
	v_mov_b32_e32 v89, v80
	v_mov_b32_e32 v90, v80
	v_mov_b32_e32 v91, v80
	v_mov_b32_e32 v92, v80
	v_mov_b32_e32 v93, v80
	v_mov_b32_e32 v94, v80
	v_mov_b32_e32 v95, v80
	v_mov_b32_e32 v64, v80
	v_mov_b32_e32 v166, v80
	v_mov_b32_e32 v168, v80
	v_mov_b32_e32 v169, v80
	v_mov_b32_e32 v170, v80
	v_mov_b32_e32 v171, v80
	v_mov_b32_e32 v172, v80
	v_mov_b32_e32 v180, v80
	v_mov_b32_e32 v182, v80
	v_mov_b32_e32 v183, v80

; #define MFMA(a, b, c) __builtin_amdgcn_mfma_f32_32x32x16_bf16((a), (b), (c), 0, 0, 0)
; DI int crow(int reg, int h) { return (reg & 3) + 8 * (reg >> 2) + 4 * h; }
; DI float fexp2(float x) { return __builtin_amdgcn_exp2f(x); }
; DI float mx2(float a, float b) { return __builtin_elementwise_maximum(a, b); }
; DI float hmax(float v) { auto rr = __builtin_amdgcn_permlane32_swap(__float_as_uint(v), __float_as_uint(v), false, false); return mx2(__uint_as_float(rr[0]), __uint_as_float(rr[1])); }
; template <int DV>
; DI void attn_core(const u16* __restrict__ P, size_t tokbase, int kcol, int vcol, int n1, int n2, int xs0,
;                   bool win, int tq, float m0, float l0, f32x16 (&o)[DV / 32], float& lsum, char* lds) {
;     ...
;     for (int ks = 0; ks < 2; ++ks) {
;       f32x16 pt = negm;
; #pragma unroll
;       for (int s = 0; s < 4; ++s) {
;         const int ch = 2 * s + h, key = 32 * ks + r;
;         const bf16x8 kf = *(const bf16x8*)(base + ch * 1024 + ((key ^ ch) * 16));
;         const bf16x8 qf = qreg[s];
;         pt = MFMA(kf, qf, pt);
;       }
;       if (domask) {
; #pragma unroll
;         for (int reg = 0; reg < 16; ++reg) {
;           const int d = tq - (kt0 + 32 * ks + crow(reg, h));
;           if (d > 128 || d < -128) pt[reg] = -1e30f;
;         }
;       }
;       float mloc = mx2(pt[0], pt[1]);
; #pragma unroll
;       for (int reg = 2; reg < 16; reg += 2) mloc = mx2(mx2(mloc, pt[reg]), pt[reg + 1]);
;       mloc = hmax(mloc);
;       const bool first = autoinit && it == 0 && ks == 0;
;       if (first || __builtin_amdgcn_ballot_w64(mloc > THR) != 0) {
;         const float d = first ? mloc : fmaxf(mloc, 0.f);
;         const float alpha = fexp2(-d);
;         m += d; l *= alpha;
; #pragma unroll
;         for (int reg = 0; reg < 16; ++reg) { negm[reg] = -m; pt[reg] -= d; }
; #pragma unroll
;         for (int b = 0; b < DV / 32; ++b)
; #pragma unroll
;           for (int reg = 0; reg < 16; ++reg) o[b][reg] *= alpha;
;       }
;       float la = 0.f;
; #pragma unroll
;       for (int reg = 0; reg < 16; ++reg) { const float e = fexp2(pt[reg]); pt[reg] = e; la += e; }
;       l += la;
.LBB0_364:
	v_add_f32_e32 v78, v97, v96
	v_add_f32_e32 v78, v98, v78
	v_add_f32_e32 v78, v99, v78
	v_add_f32_e32 v78, v100, v78
	v_add_f32_e32 v78, v101, v78
	v_add_f32_e32 v78, v102, v78
	v_add_f32_e32 v78, v103, v78
	v_add_f32_e32 v78, v104, v78
	v_add_f32_e32 v78, v105, v78
	v_add_f32_e32 v78, v106, v78
	v_add_f32_e32 v78, v107, v78
	v_add_f32_e32 v78, v108, v78
	v_add_f32_e32 v78, v109, v78
	v_add_f32_e32 v78, v110, v78
	v_add_f32_e32 v78, v111, v78
	v_add_f32_e32 v78, v186, v78
	ds_read_b128 v[186:189], v167 offset:24576
	s_waitcnt lgkmcnt(0)
	v_mfma_f32_32x32x16_bf16 v[96:111], v[186:189], v[112:115], v[80:95]
	ds_read_b128 v[186:189], v173 offset:24576
	s_waitcnt lgkmcnt(0)
	v_mfma_f32_32x32x16_bf16 v[96:111], v[186:189], v[116:119], v[96:111]
	ds_read_b128 v[186:189], v181 offset:24576
	s_waitcnt lgkmcnt(0)
	v_mfma_f32_32x32x16_bf16 v[96:111], v[186:189], v[120:123], v[96:111]
	ds_read_b128 v[186:189], v184 offset:24576
	s_waitcnt lgkmcnt(0)
	v_mfma_f32_32x32x16_bf16 v[96:111], v[186:189], v[124:127], v[96:111]
	s_nop 11
	v_maximum3_f32 v79, v96, v97, v97
	v_maximum3_f32 v79, v79, v98, v99
	v_maximum3_f32 v79, v79, v100, v101
	v_maximum3_f32 v79, v79, v102, v103
	v_maximum3_f32 v79, v79, v104, v105
	v_maximum3_f32 v79, v79, v106, v107
	v_maximum3_f32 v79, v79, v108, v109
	v_maximum3_f32 v79, v79, v110, v111
	v_mov_b32_e32 v144, v79
	s_nop 1
	v_permlane32_swap_b32_e32 v79, v144
	v_maximum3_f32 v79, v79, v144, v144
	v_cmp_lt_f32_e32 vcc, s80, v79
	s_cbranch_vccz .LBB0_366
	v_max_f32_e32 v64, v79, v79
	v_max_f32_e32 v64, 0, v64
	v_exp_f32_e64 v82, -v64
	v_add_f32_e32 v165, v165, v64
	v_xor_b32_e32 v80, 0x80000000, v165
	v_pk_add_f32 v[96:97], v[96:97], v[64:65] op_sel_hi:[1,0] neg_lo:[0,1] neg_hi:[0,1]
	v_mul_f32_e32 v78, v78, v82
	v_pk_add_f32 v[98:99], v[98:99], v[64:65] op_sel_hi:[1,0] neg_lo:[0,1] neg_hi:[0,1]
	v_pk_add_f32 v[100:101], v[100:101], v[64:65] op_sel_hi:[1,0] neg_lo:[0,1] neg_hi:[0,1]
	v_pk_add_f32 v[102:103], v[102:103], v[64:65] op_sel_hi:[1,0] neg_lo:[0,1] neg_hi:[0,1]
	v_pk_add_f32 v[104:105], v[104:105], v[64:65] op_sel_hi:[1,0] neg_lo:[0,1] neg_hi:[0,1]
	v_pk_add_f32 v[106:107], v[106:107], v[64:65] op_sel_hi:[1,0] neg_lo:[0,1] neg_hi:[0,1]
	v_pk_add_f32 v[108:109], v[108:109], v[64:65] op_sel_hi:[1,0] neg_lo:[0,1] neg_hi:[0,1]
	v_pk_add_f32 v[110:111], v[110:111], v[64:65] op_sel_hi:[1,0] neg_lo:[0,1] neg_hi:[0,1]
	v_pk_mul_f32 v[62:63], v[62:63], v[82:83] op_sel_hi:[1,0]
	v_pk_mul_f32 v[60:61], v[60:61], v[82:83] op_sel_hi:[1,0]
	v_pk_mul_f32 v[58:59], v[58:59], v[82:83] op_sel_hi:[1,0]
	v_pk_mul_f32 v[56:57], v[56:57], v[82:83] op_sel_hi:[1,0]
	v_pk_mul_f32 v[54:55], v[54:55], v[82:83] op_sel_hi:[1,0]
	v_pk_mul_f32 v[52:53], v[52:53], v[82:83] op_sel_hi:[1,0]
	v_pk_mul_f32 v[50:51], v[50:51], v[82:83] op_sel_hi:[1,0]
	v_pk_mul_f32 v[48:49], v[48:49], v[82:83] op_sel_hi:[1,0]
	v_pk_mul_f32 v[46:47], v[46:47], v[82:83] op_sel_hi:[1,0]
	v_pk_mul_f32 v[44:45], v[44:45], v[82:83] op_sel_hi:[1,0]
	v_pk_mul_f32 v[42:43], v[42:43], v[82:83] op_sel_hi:[1,0]
	v_pk_mul_f32 v[40:41], v[40:41], v[82:83] op_sel_hi:[1,0]
	v_pk_mul_f32 v[38:39], v[38:39], v[82:83] op_sel_hi:[1,0]
	v_pk_mul_f32 v[36:37], v[36:37], v[82:83] op_sel_hi:[1,0]
	v_pk_mul_f32 v[34:35], v[34:35], v[82:83] op_sel_hi:[1,0]
	v_pk_mul_f32 v[32:33], v[32:33], v[82:83] op_sel_hi:[1,0]
	v_pk_mul_f32 v[30:31], v[30:31], v[82:83] op_sel_hi:[1,0]
	v_pk_mul_f32 v[28:29], v[28:29], v[82:83] op_sel_hi:[1,0]
	v_pk_mul_f32 v[26:27], v[26:27], v[82:83] op_sel_hi:[1,0]
	v_pk_mul_f32 v[24:25], v[24:25], v[82:83] op_sel_hi:[1,0]
	v_pk_mul_f32 v[22:23], v[22:23], v[82:83] op_sel_hi:[1,0]
	v_pk_mul_f32 v[20:21], v[20:21], v[82:83] op_sel_hi:[1,0]
	v_pk_mul_f32 v[18:19], v[18:19], v[82:83] op_sel_hi:[1,0]
	v_pk_mul_f32 v[16:17], v[16:17], v[82:83] op_sel_hi:[1,0]
	v_pk_mul_f32 v[14:15], v[14:15], v[82:83] op_sel_hi:[1,0]
	v_pk_mul_f32 v[12:13], v[12:13], v[82:83] op_sel_hi:[1,0]
	v_pk_mul_f32 v[10:11], v[10:11], v[82:83] op_sel_hi:[1,0]
	v_pk_mul_f32 v[8:9], v[8:9], v[82:83] op_sel_hi:[1,0]
	v_pk_mul_f32 v[6:7], v[6:7], v[82:83] op_sel_hi:[1,0]
	v_pk_mul_f32 v[4:5], v[4:5], v[82:83] op_sel_hi:[1,0]
	v_pk_mul_f32 v[2:3], v[2:3], v[82:83] op_sel_hi:[1,0]
	v_pk_mul_f32 v[0:1], v[0:1], v[82:83] op_sel_hi:[1,0]
	v_mov_b32_e32 v81, v80
	v_mov_b32_e32 v82, v80
	v_mov_b32_e32 v83, v80
	v_mov_b32_e32 v84, v80
	v_mov_b32_e32 v85, v80
	v_mov_b32_e32 v86, v80
	v_mov_b32_e32 v87, v80
	v_mov_b32_e32 v88, v80
	v_mov_b32_e32 v89, v80
	v_mov_b32_e32 v90, v80
	v_mov_b32_e32 v91, v80
	v_mov_b32_e32 v92, v80
	v_mov_b32_e32 v93, v80
	v_mov_b32_e32 v94, v80
	v_mov_b32_e32 v95, v80
	v_mov_b32_e32 v64, v80
	v_mov_b32_e32 v166, v80
	v_mov_b32_e32 v168, v80
	v_mov_b32_e32 v169, v80
	v_mov_b32_e32 v170, v80
	v_mov_b32_e32 v171, v80
	v_mov_b32_e32 v172, v80
	v_mov_b32_e32 v180, v80
	v_mov_b32_e32 v182, v80
	v_mov_b32_e32 v183, v80
; #define MFMA(a, b, c) __builtin_amdgcn_mfma_f32_32x32x16_bf16((a), (b), (c), 0, 0, 0)
; DI int crow(int reg, int h) { return (reg & 3) + 8 * (reg >> 2) + 4 * h; }
; DI s16x4 vtr(const char* p) { return __builtin_bit_cast(s16x4, __builtin_amdgcn_ds_read_tr16_b64_v4i16((__attribute__((address_space(3))) v4i16_t*)(lds_cptr)p)); }
; template <int DV>
; DI void attn_core(const u16* __restrict__ P, size_t tokbase, int kcol, int vcol, int n1, int n2, int xs0,
;                   bool win, int tq, float m0, float l0, f32x16 (&o)[DV / 32], float& lsum, char* lds) {
;     ...
;     for (int ks = 0; ks < 2; ++ks) {
;       f32x16 pt = negm;
; #pragma unroll
;       for (int s = 0; s < 4; ++s) {
;         const int ch = 2 * s + h, key = 32 * ks + r;
;         const bf16x8 kf = *(const bf16x8*)(base + ch * 1024 + ((key ^ ch) * 16));
;         const bf16x8 qf = qreg[s];
;         pt = MFMA(kf, qf, pt);
;       }
;       if (domask) {
; #pragma unroll
;         for (int reg = 0; reg < 16; ++reg) {
;           const int d = tq - (kt0 + 32 * ks + crow(reg, h));
;           if (d > 128 || d < -128) pt[reg] = -1e30f;
;         }
;       }
;       float mloc = mx2(pt[0], pt[1]);
; #pragma unroll
;       for (int reg = 2; reg < 16; reg += 2) mloc = mx2(mx2(mloc, pt[reg]), pt[reg + 1]);
;       mloc = hmax(mloc);
;       const bool first = autoinit && it == 0 && ks == 0;
;       if (first || __builtin_amdgcn_ballot_w64(mloc > THR) != 0) {
;         const float d = first ? mloc : fmaxf(mloc, 0.f);
;         const float alpha = fexp2(-d);
;         m += d; l *= alpha;
; #pragma unroll
;         for (int reg = 0; reg < 16; ++reg) { negm[reg] = -m; pt[reg] -= d; }
; #pragma unroll
;         for (int b = 0; b < DV / 32; ++b)
; #pragma unroll
;           for (int reg = 0; reg < 16; ++reg) o[b][reg] *= alpha;
;       }
;       float la = 0.f;
; #pragma unroll
;       for (int reg = 0; reg < 16; ++reg) { const float e = fexp2(pt[reg]); pt[reg] = e; la += e; }
;       l += la;
; #pragma unroll
;       for (int s2 = 0; s2 < 2; ++s2) {
;         const bf16x8 pb = pack8(pt, s2);
;         const int s16 = 2 * ks + s2;
; #pragma unroll
;         for (int b = 0; b < DV / 32; ++b) {
;           const char* va = base + KB + b * 4096 + s16 * 1024 + trofs;
;           const bf16x8 vf = cat8(vtr(va), vtr(va + 512));
;           o[b] = MFMA(vf, pb, o[b]);
;         }
;       }
.LBB0_366:
	v_exp_f32_e32 v79, v96
	v_exp_f32_e32 v97, v97
	v_exp_f32_e32 v98, v98
	v_exp_f32_e32 v99, v99
	v_exp_f32_e32 v100, v100
	v_add_f32_e32 v96, v97, v79
	v_exp_f32_e32 v101, v101
	v_add_f32_e32 v96, v98, v96
	v_exp_f32_e32 v102, v102
	v_add_f32_e32 v96, v99, v96
	v_exp_f32_e32 v103, v103
	v_add_f32_e32 v96, v100, v96
	v_exp_f32_e32 v104, v104
	v_add_f32_e32 v96, v101, v96
	v_exp_f32_e32 v105, v105
	v_add_f32_e32 v96, v102, v96
	v_exp_f32_e32 v106, v106
	v_add_f32_e32 v96, v103, v96
	v_exp_f32_e32 v107, v107
	v_add_f32_e32 v96, v104, v96
	v_exp_f32_e32 v108, v108
	v_add_f32_e32 v96, v105, v96
	v_exp_f32_e32 v109, v109
	v_add_f32_e32 v96, v106, v96
	v_exp_f32_e32 v110, v110
	v_add_f32_e32 v96, v107, v96
	v_exp_f32_e32 v111, v111
	v_add_f32_e32 v96, v108, v96
	v_add_f32_e32 v96, v109, v96
	v_add_f32_e32 v96, v110, v96
	v_add_f32_e32 v96, v111, v96
	v_add_f32_e32 v78, v78, v96
	v_cvt_pk_bf16_f32 v96, v79, v97
	v_cvt_pk_bf16_f32 v97, v98, v99
	v_cvt_pk_bf16_f32 v98, v100, v101
	v_cvt_pk_bf16_f32 v99, v102, v103
	ds_read_b64_tr_b16 v[100:101], v159 offset:32768
	ds_read_b64_tr_b16 v[102:103], v159 offset:33280
	s_waitcnt lgkmcnt(0)
	v_mfma_f32_32x32x16_bf16 v[48:63], v[100:103], v[96:99], v[48:63]
	ds_read_b64_tr_b16 v[100:101], v159 offset:36864
	ds_read_b64_tr_b16 v[102:103], v159 offset:37376
	s_waitcnt lgkmcnt(0)
	v_mfma_f32_32x32x16_bf16 v[32:47], v[100:103], v[96:99], v[32:47]
	ds_read_b64_tr_b16 v[100:101], v159 offset:40960
	ds_read_b64_tr_b16 v[102:103], v159 offset:41472
	s_waitcnt lgkmcnt(0)
	v_mfma_f32_32x32x16_bf16 v[16:31], v[100:103], v[96:99], v[16:31]
	ds_read_b64_tr_b16 v[100:101], v159 offset:45056
	ds_read_b64_tr_b16 v[102:103], v159 offset:45568
	s_waitcnt lgkmcnt(0)
	v_mfma_f32_32x32x16_bf16 v[0:15], v[100:103], v[96:99], v[0:15]
	ds_read_b64_tr_b16 v[100:101], v159 offset:33792
	ds_read_b64_tr_b16 v[102:103], v159 offset:34304
	v_cvt_pk_bf16_f32 v96, v104, v105
	v_cvt_pk_bf16_f32 v97, v106, v107
	v_cvt_pk_bf16_f32 v98, v108, v109
	v_cvt_pk_bf16_f32 v99, v110, v111
	s_waitcnt lgkmcnt(0)
	s_nop 0
	v_mfma_f32_32x32x16_bf16 v[48:63], v[100:103], v[96:99], v[48:63]
	ds_read_b64_tr_b16 v[100:101], v159 offset:37888
	ds_read_b64_tr_b16 v[102:103], v159 offset:38400
	s_waitcnt lgkmcnt(0)
	v_mfma_f32_32x32x16_bf16 v[32:47], v[100:103], v[96:99], v[32:47]
	ds_read_b64_tr_b16 v[100:101], v159 offset:41984
	ds_read_b64_tr_b16 v[102:103], v159 offset:42496
	s_waitcnt lgkmcnt(0)
	v_mfma_f32_32x32x16_bf16 v[16:31], v[100:103], v[96:99], v[16:31]
	ds_read_b64_tr_b16 v[100:101], v159 offset:46080
	ds_read_b64_tr_b16 v[102:103], v159 offset:46592
	ds_read_b128 v[186:189], v164 offset:24576
	s_waitcnt lgkmcnt(1)
	v_mfma_f32_32x32x16_bf16 v[0:15], v[100:103], v[96:99], v[0:15]
	ds_read_b128 v[168:171], v161 offset:24576
	s_waitcnt lgkmcnt(0)
	v_mfma_f32_32x32x16_bf16 v[96:111], v[168:171], v[112:115], v[80:95]
	ds_read_b128 v[168:171], v162 offset:24576
	s_waitcnt lgkmcnt(0)
	v_mfma_f32_32x32x16_bf16 v[96:111], v[168:171], v[116:119], v[96:111]
	ds_read_b128 v[168:171], v163 offset:24576
	s_waitcnt lgkmcnt(0)
	v_mfma_f32_32x32x16_bf16 v[96:111], v[168:171], v[120:123], v[96:111]
	v_mfma_f32_32x32x16_bf16 v[96:111], v[186:189], v[124:127], v[96:111]
	s_nop 11
	v_maximum3_f32 v79, v96, v97, v97
	v_maximum3_f32 v79, v79, v98, v99
	v_maximum3_f32 v79, v79, v100, v101
	v_maximum3_f32 v79, v79, v102, v103
	v_maximum3_f32 v79, v79, v104, v105
	v_maximum3_f32 v79, v79, v106, v107
	v_maximum3_f32 v79, v79, v108, v109
	v_maximum3_f32 v79, v79, v110, v111
	v_mov_b32_e32 v166, v79
	s_nop 1
	v_permlane32_swap_b32_e32 v79, v166
	v_maximum3_f32 v79, v79, v166, v166
	v_cmp_lt_f32_e32 vcc, s80, v79
	s_cbranch_vccz .LBB0_369
	v_max_f32_e32 v64, v79, v79
	v_max_f32_e32 v64, 0, v64
	v_exp_f32_e64 v82, -v64
	v_add_f32_e32 v165, v165, v64
	v_xor_b32_e32 v80, 0x80000000, v165
	v_pk_add_f32 v[96:97], v[96:97], v[64:65] op_sel_hi:[1,0] neg_lo:[0,1] neg_hi:[0,1]
	v_mul_f32_e32 v78, v78, v82
	v_pk_add_f32 v[98:99], v[98:99], v[64:65] op_sel_hi:[1,0] neg_lo:[0,1] neg_hi:[0,1]
	v_pk_add_f32 v[100:101], v[100:101], v[64:65] op_sel_hi:[1,0] neg_lo:[0,1] neg_hi:[0,1]
	v_pk_add_f32 v[102:103], v[102:103], v[64:65] op_sel_hi:[1,0] neg_lo:[0,1] neg_hi:[0,1]
	v_pk_add_f32 v[104:105], v[104:105], v[64:65] op_sel_hi:[1,0] neg_lo:[0,1] neg_hi:[0,1]
	v_pk_add_f32 v[106:107], v[106:107], v[64:65] op_sel_hi:[1,0] neg_lo:[0,1] neg_hi:[0,1]
	v_pk_add_f32 v[108:109], v[108:109], v[64:65] op_sel_hi:[1,0] neg_lo:[0,1] neg_hi:[0,1]
	v_pk_add_f32 v[110:111], v[110:111], v[64:65] op_sel_hi:[1,0] neg_lo:[0,1] neg_hi:[0,1]
	v_pk_mul_f32 v[62:63], v[62:63], v[82:83] op_sel_hi:[1,0]
	v_pk_mul_f32 v[60:61], v[60:61], v[82:83] op_sel_hi:[1,0]
	v_pk_mul_f32 v[58:59], v[58:59], v[82:83] op_sel_hi:[1,0]
	v_pk_mul_f32 v[56:57], v[56:57], v[82:83] op_sel_hi:[1,0]
	v_pk_mul_f32 v[54:55], v[54:55], v[82:83] op_sel_hi:[1,0]
	v_pk_mul_f32 v[52:53], v[52:53], v[82:83] op_sel_hi:[1,0]
	v_pk_mul_f32 v[50:51], v[50:51], v[82:83] op_sel_hi:[1,0]
	v_pk_mul_f32 v[48:49], v[48:49], v[82:83] op_sel_hi:[1,0]
	v_pk_mul_f32 v[46:47], v[46:47], v[82:83] op_sel_hi:[1,0]
	v_pk_mul_f32 v[44:45], v[44:45], v[82:83] op_sel_hi:[1,0]
	v_pk_mul_f32 v[42:43], v[42:43], v[82:83] op_sel_hi:[1,0]
	v_pk_mul_f32 v[40:41], v[40:41], v[82:83] op_sel_hi:[1,0]
	v_pk_mul_f32 v[38:39], v[38:39], v[82:83] op_sel_hi:[1,0]
	v_pk_mul_f32 v[36:37], v[36:37], v[82:83] op_sel_hi:[1,0]
	v_pk_mul_f32 v[34:35], v[34:35], v[82:83] op_sel_hi:[1,0]
	v_pk_mul_f32 v[32:33], v[32:33], v[82:83] op_sel_hi:[1,0]
	v_pk_mul_f32 v[30:31], v[30:31], v[82:83] op_sel_hi:[1,0]
	v_pk_mul_f32 v[28:29], v[28:29], v[82:83] op_sel_hi:[1,0]
	v_pk_mul_f32 v[26:27], v[26:27], v[82:83] op_sel_hi:[1,0]
	v_pk_mul_f32 v[24:25], v[24:25], v[82:83] op_sel_hi:[1,0]
	v_pk_mul_f32 v[22:23], v[22:23], v[82:83] op_sel_hi:[1,0]
	v_pk_mul_f32 v[20:21], v[20:21], v[82:83] op_sel_hi:[1,0]
	v_pk_mul_f32 v[18:19], v[18:19], v[82:83] op_sel_hi:[1,0]
	v_pk_mul_f32 v[16:17], v[16:17], v[82:83] op_sel_hi:[1,0]
	v_pk_mul_f32 v[14:15], v[14:15], v[82:83] op_sel_hi:[1,0]
	v_pk_mul_f32 v[12:13], v[12:13], v[82:83] op_sel_hi:[1,0]
	v_pk_mul_f32 v[10:11], v[10:11], v[82:83] op_sel_hi:[1,0]
	v_pk_mul_f32 v[8:9], v[8:9], v[82:83] op_sel_hi:[1,0]
	v_pk_mul_f32 v[6:7], v[6:7], v[82:83] op_sel_hi:[1,0]
	v_pk_mul_f32 v[4:5], v[4:5], v[82:83] op_sel_hi:[1,0]
	v_pk_mul_f32 v[2:3], v[2:3], v[82:83] op_sel_hi:[1,0]
	v_pk_mul_f32 v[0:1], v[0:1], v[82:83] op_sel_hi:[1,0]
	v_mov_b32_e32 v81, v80
	v_mov_b32_e32 v82, v80
	v_mov_b32_e32 v83, v80
	v_mov_b32_e32 v84, v80
	v_mov_b32_e32 v85, v80
	v_mov_b32_e32 v86, v80
	v_mov_b32_e32 v87, v80
	v_mov_b32_e32 v88, v80
	v_mov_b32_e32 v89, v80
	v_mov_b32_e32 v90, v80
	v_mov_b32_e32 v91, v80
	v_mov_b32_e32 v92, v80
	v_mov_b32_e32 v93, v80
	v_mov_b32_e32 v94, v80
	v_mov_b32_e32 v95, v80
	s_branch .LBB0_370

; DI float fexp2(float x) { return __builtin_amdgcn_exp2f(x); }
; template <int DV>
; DI void attn_core(const u16* __restrict__ P, size_t tokbase, int kcol, int vcol, int n1, int n2, int xs0,
;                   bool win, int tq, float m0, float l0, f32x16 (&o)[DV / 32], float& lsum, char* lds) {
;     ...
;       float la = 0.f;
; #pragma unroll
;       for (int reg = 0; reg < 16; ++reg) { const float e = fexp2(pt[reg]); pt[reg] = e; la += e; }
;       l += la;
;     ...
;     for (int it = 0; it < ntiles; it += 2) {
;       if (it + 2 < ntiles) A_LOAD(kA, vA, it + 2);
;       compute(lds, it);
;       A_STORE(kB, vB, 1);
;       __syncthreads();
;       if (it + 3 < ntiles) A_LOAD(kB, vB, it + 3);
;       compute(lds + STAGE, it + 1);
;       if (it + 2 < ntiles) A_STORE(kA, vA, 0);
;       __syncthreads();
.LBB0_373:
	v_add_f32_e32 v82, v83, v82
	v_add_f32_e32 v82, v84, v82
	v_add_f32_e32 v82, v85, v82
	v_add_f32_e32 v82, v86, v82
	v_add_f32_e32 v82, v87, v82
	v_add_f32_e32 v82, v88, v82
	v_add_f32_e32 v82, v89, v82
	v_add_f32_e32 v82, v90, v82
	v_add_f32_e32 v82, v91, v82
	v_add_f32_e32 v82, v92, v82
	v_add_f32_e32 v82, v93, v82
	v_add_f32_e32 v82, v94, v82
	v_add_f32_e32 v82, v95, v82
	v_add_f32_e32 v82, v96, v82
	s_add_i32 s26, s26, 2
	v_add_f32_e32 v82, v97, v82
	s_add_u32 s28, s28, 0x172000
	v_add_f32_e32 v186, v144, v82
	s_addc_u32 s29, s29, 0
	s_andn2_b64 vcc, exec, s[0:1]
	s_waitcnt lgkmcnt(0)
	s_barrier
	s_cbranch_vccz .LBB0_394

; #define MFMA(a, b, c) __builtin_amdgcn_mfma_f32_32x32x16_bf16((a), (b), (c), 0, 0, 0)
; DI int crow(int reg, int h) { return (reg & 3) + 8 * (reg >> 2) + 4 * h; }
; DI s16x4 vtr(const char* p) { return __builtin_bit_cast(s16x4, __builtin_amdgcn_ds_read_tr16_b64_v4i16((__attribute__((address_space(3))) v4i16_t*)(lds_cptr)p)); }
; template <int DV>
; DI void attn_core(const u16* __restrict__ P, size_t tokbase, int kcol, int vcol, int n1, int n2, int xs0,
;                   bool win, int tq, float m0, float l0, f32x16 (&o)[DV / 32], float& lsum, char* lds) {
;     ...
;     for (int ks = 0; ks < 2; ++ks) {
;       f32x16 pt = negm;
; #pragma unroll
;       for (int s = 0; s < 4; ++s) {
;         const int ch = 2 * s + h, key = 32 * ks + r;
;         const bf16x8 kf = *(const bf16x8*)(base + ch * 1024 + ((key ^ ch) * 16));
;         const bf16x8 qf = qreg[s];
;         pt = MFMA(kf, qf, pt);
;       }
;       if (domask) {
; #pragma unroll
;         for (int reg = 0; reg < 16; ++reg) {
;           const int d = tq - (kt0 + 32 * ks + crow(reg, h));
;           if (d > 128 || d < -128) pt[reg] = -1e30f;
;         }
;       }
;       float mloc = mx2(pt[0], pt[1]);
; #pragma unroll
;       for (int reg = 2; reg < 16; reg += 2) mloc = mx2(mx2(mloc, pt[reg]), pt[reg + 1]);
;       mloc = hmax(mloc);
;       const bool first = autoinit && it == 0 && ks == 0;
;       if (first || __builtin_amdgcn_ballot_w64(mloc > THR) != 0) {
;         const float d = first ? mloc : fmaxf(mloc, 0.f);
;         const float alpha = fexp2(-d);
;         m += d; l *= alpha;
; #pragma unroll
;         for (int reg = 0; reg < 16; ++reg) { negm[reg] = -m; pt[reg] -= d; }
; #pragma unroll
;         for (int b = 0; b < DV / 32; ++b)
; #pragma unroll
;           for (int reg = 0; reg < 16; ++reg) o[b][reg] *= alpha;
;       }
;       float la = 0.f;
; #pragma unroll
;       for (int reg = 0; reg < 16; ++reg) { const float e = fexp2(pt[reg]); pt[reg] = e; la += e; }
;       l += la;
; #pragma unroll
;       for (int s2 = 0; s2 < 2; ++s2) {
;         const bf16x8 pb = pack8(pt, s2);
;         const int s16 = 2 * ks + s2;
; #pragma unroll
;         for (int b = 0; b < DV / 32; ++b) {
;           const char* va = base + KB + b * 4096 + s16 * 1024 + trofs;
;           const bf16x8 vf = cat8(vtr(va), vtr(va + 512));
;           o[b] = MFMA(vf, pb, o[b]);
;         }
;       }
.LBB0_381:
.LBB0_382:
	v_exp_f32_e32 v82, v82
	v_exp_f32_e32 v83, v83
	v_exp_f32_e32 v84, v84
	v_exp_f32_e32 v85, v85
	v_exp_f32_e32 v86, v86
	v_add_f32_e32 v187, v83, v82
	v_exp_f32_e32 v87, v87
	v_add_f32_e32 v187, v84, v187
	v_exp_f32_e32 v88, v88
	v_add_f32_e32 v187, v85, v187
	v_exp_f32_e32 v89, v89
	v_add_f32_e32 v187, v86, v187
	v_add_f32_e32 v187, v87, v187
	v_add_f32_e32 v187, v88, v187
	v_add_f32_e32 v187, v89, v187
	v_cvt_pk_bf16_f32 v82, v82, v83
	v_cvt_pk_bf16_f32 v83, v84, v85
	v_cvt_pk_bf16_f32 v84, v86, v87
	v_cvt_pk_bf16_f32 v85, v88, v89
	ds_read_b64_tr_b16 v[86:87], v157 offset:8192
	ds_read_b64_tr_b16 v[88:89], v157 offset:8704
	s_waitcnt lgkmcnt(0)
	v_mfma_f32_32x32x16_bf16 v[48:63], v[86:89], v[82:85], v[48:63]
	ds_read_b64_tr_b16 v[86:87], v157 offset:12288
	ds_read_b64_tr_b16 v[88:89], v157 offset:12800
	v_exp_f32_e32 v90, v90
	v_exp_f32_e32 v91, v91
	v_exp_f32_e32 v92, v92
	v_exp_f32_e32 v93, v93
	v_exp_f32_e32 v94, v94
	v_exp_f32_e32 v95, v95
	s_waitcnt lgkmcnt(0)
	v_mfma_f32_32x32x16_bf16 v[32:47], v[86:89], v[82:85], v[32:47]
	ds_read_b64_tr_b16 v[86:87], v157 offset:16384
	ds_read_b64_tr_b16 v[88:89], v157 offset:16896
	v_exp_f32_e32 v96, v96
	v_exp_f32_e32 v97, v97
	v_add_f32_e32 v187, v90, v187
	v_add_f32_e32 v187, v91, v187
	v_add_f32_e32 v187, v92, v187
	v_add_f32_e32 v187, v93, v187
	s_waitcnt lgkmcnt(0)
	v_mfma_f32_32x32x16_bf16 v[16:31], v[86:89], v[82:85], v[16:31]
	ds_read_b64_tr_b16 v[86:87], v157 offset:20480
	ds_read_b64_tr_b16 v[88:89], v157 offset:20992
	v_add_f32_e32 v187, v94, v187
	v_add_f32_e32 v187, v95, v187
	v_add_f32_e32 v187, v96, v187
	v_add_f32_e32 v187, v97, v187
	v_add_f32_e32 v187, v186, v187
	s_waitcnt lgkmcnt(0)
	v_mfma_f32_32x32x16_bf16 v[0:15], v[86:89], v[82:85], v[0:15]
	ds_read_b64_tr_b16 v[86:87], v157 offset:9216
	ds_read_b64_tr_b16 v[88:89], v157 offset:9728
	v_cvt_pk_bf16_f32 v82, v90, v91
	v_cvt_pk_bf16_f32 v83, v92, v93
	v_cvt_pk_bf16_f32 v84, v94, v95
	v_cvt_pk_bf16_f32 v85, v96, v97
	s_waitcnt lgkmcnt(0)
	s_nop 0
	v_mfma_f32_32x32x16_bf16 v[48:63], v[86:89], v[82:85], v[48:63]
	ds_read_b64_tr_b16 v[86:87], v157 offset:13312
	ds_read_b64_tr_b16 v[88:89], v157 offset:13824
	s_waitcnt lgkmcnt(0)
	v_mfma_f32_32x32x16_bf16 v[32:47], v[86:89], v[82:85], v[32:47]
	ds_read_b64_tr_b16 v[86:87], v157 offset:17408
	ds_read_b64_tr_b16 v[88:89], v157 offset:17920
	s_waitcnt lgkmcnt(0)
	v_mfma_f32_32x32x16_bf16 v[16:31], v[86:89], v[82:85], v[16:31]
	ds_read_b64_tr_b16 v[86:87], v157 offset:21504
	ds_read_b64_tr_b16 v[88:89], v157 offset:22016
	ds_read_b128 v[206:209], v162
	s_waitcnt lgkmcnt(1)
	v_mfma_f32_32x32x16_bf16 v[0:15], v[86:89], v[82:85], v[0:15]
	s_waitcnt lgkmcnt(0)
	v_mfma_f32_32x32x16_bf16 v[82:97], v[206:209], v[98:101], v[66:81]
	ds_read_b128 v[206:209], v163
	s_waitcnt lgkmcnt(0)
	v_mfma_f32_32x32x16_bf16 v[82:97], v[206:209], v[102:105], v[82:97]
	ds_read_b128 v[206:209], v164
	s_waitcnt lgkmcnt(0)
	v_mfma_f32_32x32x16_bf16 v[82:97], v[206:209], v[106:109], v[82:97]
	ds_read_b128 v[206:209], v165
	s_waitcnt lgkmcnt(0)
	v_mfma_f32_32x32x16_bf16 v[82:97], v[206:209], v[110:113], v[82:97]
	s_nop 11
	v_maximum3_f32 v186, v82, v83, v83
	v_maximum3_f32 v186, v186, v84, v85
	v_maximum3_f32 v186, v186, v86, v87
	v_maximum3_f32 v186, v186, v88, v89
	v_maximum3_f32 v186, v186, v90, v91
	v_maximum3_f32 v186, v186, v92, v93
	v_maximum3_f32 v186, v186, v94, v95
	v_maximum3_f32 v186, v186, v96, v97
	v_mov_b32_e32 v188, v186
	s_nop 1
	v_permlane32_swap_b32_e32 v186, v188
	v_maximum3_f32 v186, v186, v188, v188
	v_cmp_lt_f32_e32 vcc, s80, v186
	s_cbranch_vccz .LBB0_384
	v_max_f32_e32 v66, v186, v186
	v_max_f32_e32 v68, 0, v66
	v_exp_f32_e64 v70, -v68
	v_add_f32_e32 v166, v166, v68
	v_xor_b32_e32 v66, 0x80000000, v166
	v_pk_add_f32 v[82:83], v[82:83], v[68:69] op_sel_hi:[1,0] neg_lo:[0,1] neg_hi:[0,1]
	v_mul_f32_e32 v187, v187, v70
	v_pk_add_f32 v[84:85], v[84:85], v[68:69] op_sel_hi:[1,0] neg_lo:[0,1] neg_hi:[0,1]
	v_pk_add_f32 v[86:87], v[86:87], v[68:69] op_sel_hi:[1,0] neg_lo:[0,1] neg_hi:[0,1]
	v_pk_add_f32 v[88:89], v[88:89], v[68:69] op_sel_hi:[1,0] neg_lo:[0,1] neg_hi:[0,1]
	v_pk_add_f32 v[90:91], v[90:91], v[68:69] op_sel_hi:[1,0] neg_lo:[0,1] neg_hi:[0,1]
	v_pk_add_f32 v[92:93], v[92:93], v[68:69] op_sel_hi:[1,0] neg_lo:[0,1] neg_hi:[0,1]
	v_pk_add_f32 v[94:95], v[94:95], v[68:69] op_sel_hi:[1,0] neg_lo:[0,1] neg_hi:[0,1]
	v_pk_add_f32 v[96:97], v[96:97], v[68:69] op_sel_hi:[1,0] neg_lo:[0,1] neg_hi:[0,1]
	v_pk_mul_f32 v[62:63], v[62:63], v[70:71] op_sel_hi:[1,0]
	v_pk_mul_f32 v[60:61], v[60:61], v[70:71] op_sel_hi:[1,0]
	v_pk_mul_f32 v[58:59], v[58:59], v[70:71] op_sel_hi:[1,0]
	v_pk_mul_f32 v[56:57], v[56:57], v[70:71] op_sel_hi:[1,0]
	v_pk_mul_f32 v[54:55], v[54:55], v[70:71] op_sel_hi:[1,0]
	v_pk_mul_f32 v[52:53], v[52:53], v[70:71] op_sel_hi:[1,0]
	v_pk_mul_f32 v[50:51], v[50:51], v[70:71] op_sel_hi:[1,0]
	v_pk_mul_f32 v[48:49], v[48:49], v[70:71] op_sel_hi:[1,0]
	v_pk_mul_f32 v[46:47], v[46:47], v[70:71] op_sel_hi:[1,0]
	v_pk_mul_f32 v[44:45], v[44:45], v[70:71] op_sel_hi:[1,0]
	v_pk_mul_f32 v[42:43], v[42:43], v[70:71] op_sel_hi:[1,0]
	v_pk_mul_f32 v[40:41], v[40:41], v[70:71] op_sel_hi:[1,0]
	v_pk_mul_f32 v[38:39], v[38:39], v[70:71] op_sel_hi:[1,0]
	v_pk_mul_f32 v[36:37], v[36:37], v[70:71] op_sel_hi:[1,0]
	v_pk_mul_f32 v[34:35], v[34:35], v[70:71] op_sel_hi:[1,0]
	v_pk_mul_f32 v[32:33], v[32:33], v[70:71] op_sel_hi:[1,0]
	v_pk_mul_f32 v[30:31], v[30:31], v[70:71] op_sel_hi:[1,0]
	v_pk_mul_f32 v[28:29], v[28:29], v[70:71] op_sel_hi:[1,0]
	v_pk_mul_f32 v[26:27], v[26:27], v[70:71] op_sel_hi:[1,0]
	v_pk_mul_f32 v[24:25], v[24:25], v[70:71] op_sel_hi:[1,0]
	v_pk_mul_f32 v[22:23], v[22:23], v[70:71] op_sel_hi:[1,0]
	v_pk_mul_f32 v[20:21], v[20:21], v[70:71] op_sel_hi:[1,0]
	v_pk_mul_f32 v[18:19], v[18:19], v[70:71] op_sel_hi:[1,0]
	v_pk_mul_f32 v[16:17], v[16:17], v[70:71] op_sel_hi:[1,0]
	v_pk_mul_f32 v[14:15], v[14:15], v[70:71] op_sel_hi:[1,0]
	v_pk_mul_f32 v[12:13], v[12:13], v[70:71] op_sel_hi:[1,0]
	v_pk_mul_f32 v[10:11], v[10:11], v[70:71] op_sel_hi:[1,0]
	v_pk_mul_f32 v[8:9], v[8:9], v[70:71] op_sel_hi:[1,0]
	v_pk_mul_f32 v[6:7], v[6:7], v[70:71] op_sel_hi:[1,0]
	v_pk_mul_f32 v[4:5], v[4:5], v[70:71] op_sel_hi:[1,0]
	v_pk_mul_f32 v[2:3], v[2:3], v[70:71] op_sel_hi:[1,0]
	v_pk_mul_f32 v[0:1], v[0:1], v[70:71] op_sel_hi:[1,0]
	v_mov_b32_e32 v67, v66
	v_mov_b32_e32 v68, v66
	v_mov_b32_e32 v69, v66
	v_mov_b32_e32 v70, v66
	v_mov_b32_e32 v71, v66
	v_mov_b32_e32 v72, v66
	v_mov_b32_e32 v73, v66
	v_mov_b32_e32 v74, v66
	v_mov_b32_e32 v75, v66
	v_mov_b32_e32 v76, v66
	v_mov_b32_e32 v77, v66
	v_mov_b32_e32 v78, v66
	v_mov_b32_e32 v79, v66
	v_mov_b32_e32 v80, v66
	v_mov_b32_e32 v81, v66
	v_mov_b32_e32 v148, v66
	v_mov_b32_e32 v167, v66
	v_mov_b32_e32 v169, v66
	v_mov_b32_e32 v170, v66
	v_mov_b32_e32 v171, v66
	v_mov_b32_e32 v172, v66
	v_mov_b32_e32 v173, v66
	v_mov_b32_e32 v175, v66
	v_mov_b32_e32 v183, v66
	v_mov_b32_e32 v184, v66

; #define MFMA(a, b, c) __builtin_amdgcn_mfma_f32_32x32x16_bf16((a), (b), (c), 0, 0, 0)
; DI int crow(int reg, int h) { return (reg & 3) + 8 * (reg >> 2) + 4 * h; }
; DI float fexp2(float x) { return __builtin_amdgcn_exp2f(x); }
; DI float mx2(float a, float b) { return __builtin_elementwise_maximum(a, b); }
; DI float hmax(float v) { auto rr = __builtin_amdgcn_permlane32_swap(__float_as_uint(v), __float_as_uint(v), false, false); return mx2(__uint_as_float(rr[0]), __uint_as_float(rr[1])); }
; template <int DV>
; DI void attn_core(const u16* __restrict__ P, size_t tokbase, int kcol, int vcol, int n1, int n2, int xs0,
;                   bool win, int tq, float m0, float l0, f32x16 (&o)[DV / 32], float& lsum, char* lds) {
;     ...
;     for (int ks = 0; ks < 2; ++ks) {
;       f32x16 pt = negm;
; #pragma unroll
;       for (int s = 0; s < 4; ++s) {
;         const int ch = 2 * s + h, key = 32 * ks + r;
;         const bf16x8 kf = *(const bf16x8*)(base + ch * 1024 + ((key ^ ch) * 16));
;         const bf16x8 qf = qreg[s];
;         pt = MFMA(kf, qf, pt);
;       }
;       if (domask) {
; #pragma unroll
;         for (int reg = 0; reg < 16; ++reg) {
;           const int d = tq - (kt0 + 32 * ks + crow(reg, h));
;           if (d > 128 || d < -128) pt[reg] = -1e30f;
;         }
;       }
;       float mloc = mx2(pt[0], pt[1]);
; #pragma unroll
;       for (int reg = 2; reg < 16; reg += 2) mloc = mx2(mx2(mloc, pt[reg]), pt[reg + 1]);
;       mloc = hmax(mloc);
;       const bool first = autoinit && it == 0 && ks == 0;
;       if (first || __builtin_amdgcn_ballot_w64(mloc > THR) != 0) {
;         const float d = first ? mloc : fmaxf(mloc, 0.f);
;         const float alpha = fexp2(-d);
;         m += d; l *= alpha;
; #pragma unroll
;         for (int reg = 0; reg < 16; ++reg) { negm[reg] = -m; pt[reg] -= d; }
; #pragma unroll
;         for (int b = 0; b < DV / 32; ++b)
; #pragma unroll
;           for (int reg = 0; reg < 16; ++reg) o[b][reg] *= alpha;
;       }
;       float la = 0.f;
; #pragma unroll
;       for (int reg = 0; reg < 16; ++reg) { const float e = fexp2(pt[reg]); pt[reg] = e; la += e; }
;       l += la;
.LBB0_386:
	v_add_f32_e32 v82, v83, v82
	v_add_f32_e32 v82, v84, v82
	v_add_f32_e32 v82, v85, v82
	v_add_f32_e32 v82, v86, v82
	v_add_f32_e32 v82, v87, v82
	v_add_f32_e32 v82, v88, v82
	v_add_f32_e32 v82, v89, v82
	ds_read_b128 v[206:209], v168 offset:24576
	v_add_f32_e32 v82, v90, v82
	v_add_f32_e32 v82, v91, v82
	v_add_f32_e32 v82, v92, v82
	v_add_f32_e32 v82, v93, v82
	v_add_f32_e32 v82, v94, v82
	v_add_f32_e32 v82, v95, v82
	v_add_f32_e32 v82, v96, v82
	v_add_f32_e32 v82, v97, v82
	v_add_f32_e32 v144, v187, v82
	s_waitcnt lgkmcnt(0)
	v_mfma_f32_32x32x16_bf16 v[82:97], v[206:209], v[98:101], v[66:81]
	ds_read_b128 v[206:209], v174 offset:24576
	s_waitcnt lgkmcnt(0)
	v_mfma_f32_32x32x16_bf16 v[82:97], v[206:209], v[102:105], v[82:97]
	ds_read_b128 v[206:209], v182 offset:24576
	s_waitcnt lgkmcnt(0)
	v_mfma_f32_32x32x16_bf16 v[82:97], v[206:209], v[106:109], v[82:97]
	ds_read_b128 v[206:209], v185 offset:24576
	s_waitcnt lgkmcnt(0)
	v_mfma_f32_32x32x16_bf16 v[82:97], v[206:209], v[110:113], v[82:97]
	s_nop 11
	v_maximum3_f32 v145, v82, v83, v83
	v_maximum3_f32 v145, v145, v84, v85
	v_maximum3_f32 v145, v145, v86, v87
	v_maximum3_f32 v145, v145, v88, v89
	v_maximum3_f32 v145, v145, v90, v91
	v_maximum3_f32 v145, v145, v92, v93
	v_maximum3_f32 v145, v145, v94, v95
	v_maximum3_f32 v145, v145, v96, v97
	v_mov_b32_e32 v146, v145
	s_nop 1
	v_permlane32_swap_b32_e32 v145, v146
	v_maximum3_f32 v145, v145, v146, v146
	v_cmp_lt_f32_e32 vcc, s80, v145
	s_cbranch_vccz .LBB0_388
	v_max_f32_e32 v66, v145, v145
	v_max_f32_e32 v68, 0, v66
	v_exp_f32_e64 v70, -v68
	v_add_f32_e32 v166, v166, v68
	v_xor_b32_e32 v66, 0x80000000, v166
	v_pk_add_f32 v[82:83], v[82:83], v[68:69] op_sel_hi:[1,0] neg_lo:[0,1] neg_hi:[0,1]
	v_mul_f32_e32 v144, v144, v70
	v_pk_add_f32 v[84:85], v[84:85], v[68:69] op_sel_hi:[1,0] neg_lo:[0,1] neg_hi:[0,1]
	v_pk_add_f32 v[86:87], v[86:87], v[68:69] op_sel_hi:[1,0] neg_lo:[0,1] neg_hi:[0,1]
	v_pk_add_f32 v[88:89], v[88:89], v[68:69] op_sel_hi:[1,0] neg_lo:[0,1] neg_hi:[0,1]
	v_pk_add_f32 v[90:91], v[90:91], v[68:69] op_sel_hi:[1,0] neg_lo:[0,1] neg_hi:[0,1]
	v_pk_add_f32 v[92:93], v[92:93], v[68:69] op_sel_hi:[1,0] neg_lo:[0,1] neg_hi:[0,1]
	v_pk_add_f32 v[94:95], v[94:95], v[68:69] op_sel_hi:[1,0] neg_lo:[0,1] neg_hi:[0,1]
	v_pk_add_f32 v[96:97], v[96:97], v[68:69] op_sel_hi:[1,0] neg_lo:[0,1] neg_hi:[0,1]
	v_pk_mul_f32 v[62:63], v[62:63], v[70:71] op_sel_hi:[1,0]
	v_pk_mul_f32 v[60:61], v[60:61], v[70:71] op_sel_hi:[1,0]
	v_pk_mul_f32 v[58:59], v[58:59], v[70:71] op_sel_hi:[1,0]
	v_pk_mul_f32 v[56:57], v[56:57], v[70:71] op_sel_hi:[1,0]
	v_pk_mul_f32 v[54:55], v[54:55], v[70:71] op_sel_hi:[1,0]
	v_pk_mul_f32 v[52:53], v[52:53], v[70:71] op_sel_hi:[1,0]
	v_pk_mul_f32 v[50:51], v[50:51], v[70:71] op_sel_hi:[1,0]
	v_pk_mul_f32 v[48:49], v[48:49], v[70:71] op_sel_hi:[1,0]
	v_pk_mul_f32 v[46:47], v[46:47], v[70:71] op_sel_hi:[1,0]
	v_pk_mul_f32 v[44:45], v[44:45], v[70:71] op_sel_hi:[1,0]
	v_pk_mul_f32 v[42:43], v[42:43], v[70:71] op_sel_hi:[1,0]
	v_pk_mul_f32 v[40:41], v[40:41], v[70:71] op_sel_hi:[1,0]
	v_pk_mul_f32 v[38:39], v[38:39], v[70:71] op_sel_hi:[1,0]
	v_pk_mul_f32 v[36:37], v[36:37], v[70:71] op_sel_hi:[1,0]
	v_pk_mul_f32 v[34:35], v[34:35], v[70:71] op_sel_hi:[1,0]
	v_pk_mul_f32 v[32:33], v[32:33], v[70:71] op_sel_hi:[1,0]
	v_pk_mul_f32 v[30:31], v[30:31], v[70:71] op_sel_hi:[1,0]
	v_pk_mul_f32 v[28:29], v[28:29], v[70:71] op_sel_hi:[1,0]
	v_pk_mul_f32 v[26:27], v[26:27], v[70:71] op_sel_hi:[1,0]
	v_pk_mul_f32 v[24:25], v[24:25], v[70:71] op_sel_hi:[1,0]
	v_pk_mul_f32 v[22:23], v[22:23], v[70:71] op_sel_hi:[1,0]
	v_pk_mul_f32 v[20:21], v[20:21], v[70:71] op_sel_hi:[1,0]
	v_pk_mul_f32 v[18:19], v[18:19], v[70:71] op_sel_hi:[1,0]
	v_pk_mul_f32 v[16:17], v[16:17], v[70:71] op_sel_hi:[1,0]
	v_pk_mul_f32 v[14:15], v[14:15], v[70:71] op_sel_hi:[1,0]
	v_pk_mul_f32 v[12:13], v[12:13], v[70:71] op_sel_hi:[1,0]
	v_pk_mul_f32 v[10:11], v[10:11], v[70:71] op_sel_hi:[1,0]
	v_pk_mul_f32 v[8:9], v[8:9], v[70:71] op_sel_hi:[1,0]
	v_pk_mul_f32 v[6:7], v[6:7], v[70:71] op_sel_hi:[1,0]
	v_pk_mul_f32 v[4:5], v[4:5], v[70:71] op_sel_hi:[1,0]
	v_pk_mul_f32 v[2:3], v[2:3], v[70:71] op_sel_hi:[1,0]
	v_pk_mul_f32 v[0:1], v[0:1], v[70:71] op_sel_hi:[1,0]
	v_mov_b32_e32 v67, v66
	v_mov_b32_e32 v68, v66
	v_mov_b32_e32 v69, v66
	v_mov_b32_e32 v70, v66
	v_mov_b32_e32 v71, v66
	v_mov_b32_e32 v72, v66
	v_mov_b32_e32 v73, v66
	v_mov_b32_e32 v74, v66
	v_mov_b32_e32 v75, v66
	v_mov_b32_e32 v76, v66
	v_mov_b32_e32 v77, v66
	v_mov_b32_e32 v78, v66
	v_mov_b32_e32 v79, v66
	v_mov_b32_e32 v80, v66
	v_mov_b32_e32 v81, v66
	v_mov_b32_e32 v148, v66
	v_mov_b32_e32 v167, v66
	v_mov_b32_e32 v169, v66
	v_mov_b32_e32 v170, v66
	v_mov_b32_e32 v171, v66
	v_mov_b32_e32 v172, v66
	v_mov_b32_e32 v173, v66
	v_mov_b32_e32 v175, v66
	v_mov_b32_e32 v183, v66
	v_mov_b32_e32 v184, v66
; #define MFMA(a, b, c) __builtin_amdgcn_mfma_f32_32x32x16_bf16((a), (b), (c), 0, 0, 0)
; DI int crow(int reg, int h) { return (reg & 3) + 8 * (reg >> 2) + 4 * h; }
; DI s16x4 vtr(const char* p) { return __builtin_bit_cast(s16x4, __builtin_amdgcn_ds_read_tr16_b64_v4i16((__attribute__((address_space(3))) v4i16_t*)(lds_cptr)p)); }
; template <int DV>
; DI void attn_core(const u16* __restrict__ P, size_t tokbase, int kcol, int vcol, int n1, int n2, int xs0,
;                   bool win, int tq, float m0, float l0, f32x16 (&o)[DV / 32], float& lsum, char* lds) {
;     ...
;     for (int ks = 0; ks < 2; ++ks) {
;       f32x16 pt = negm;
; #pragma unroll
;       for (int s = 0; s < 4; ++s) {
;         const int ch = 2 * s + h, key = 32 * ks + r;
;         const bf16x8 kf = *(const bf16x8*)(base + ch * 1024 + ((key ^ ch) * 16));
;         const bf16x8 qf = qreg[s];
;         pt = MFMA(kf, qf, pt);
;       }
;       if (domask) {
; #pragma unroll
;         for (int reg = 0; reg < 16; ++reg) {
;           const int d = tq - (kt0 + 32 * ks + crow(reg, h));
;           if (d > 128 || d < -128) pt[reg] = -1e30f;
;         }
;       }
;       float mloc = mx2(pt[0], pt[1]);
; #pragma unroll
;       for (int reg = 2; reg < 16; reg += 2) mloc = mx2(mx2(mloc, pt[reg]), pt[reg + 1]);
;       mloc = hmax(mloc);
;       const bool first = autoinit && it == 0 && ks == 0;
;       if (first || __builtin_amdgcn_ballot_w64(mloc > THR) != 0) {
;         const float d = first ? mloc : fmaxf(mloc, 0.f);
;         const float alpha = fexp2(-d);
;         m += d; l *= alpha;
; #pragma unroll
;         for (int reg = 0; reg < 16; ++reg) { negm[reg] = -m; pt[reg] -= d; }
; #pragma unroll
;         for (int b = 0; b < DV / 32; ++b)
; #pragma unroll
;           for (int reg = 0; reg < 16; ++reg) o[b][reg] *= alpha;
;       }
;       float la = 0.f;
; #pragma unroll
;       for (int reg = 0; reg < 16; ++reg) { const float e = fexp2(pt[reg]); pt[reg] = e; la += e; }
;       l += la;
; #pragma unroll
;       for (int s2 = 0; s2 < 2; ++s2) {
;         const bf16x8 pb = pack8(pt, s2);
;         const int s16 = 2 * ks + s2;
; #pragma unroll
;         for (int b = 0; b < DV / 32; ++b) {
;           const char* va = base + KB + b * 4096 + s16 * 1024 + trofs;
;           const bf16x8 vf = cat8(vtr(va), vtr(va + 512));
;           o[b] = MFMA(vf, pb, o[b]);
;         }
;       }
.LBB0_388:
	v_exp_f32_e32 v82, v82
	v_exp_f32_e32 v83, v83
	v_exp_f32_e32 v84, v84
	v_exp_f32_e32 v85, v85
	v_exp_f32_e32 v86, v86
	v_add_f32_e32 v145, v83, v82
	v_exp_f32_e32 v87, v87
	v_add_f32_e32 v145, v84, v145
	v_exp_f32_e32 v88, v88
	v_add_f32_e32 v145, v85, v145
	v_exp_f32_e32 v89, v89
	v_add_f32_e32 v145, v86, v145
	v_add_f32_e32 v145, v87, v145
	v_add_f32_e32 v145, v88, v145
	v_add_f32_e32 v145, v89, v145
	v_cvt_pk_bf16_f32 v82, v82, v83
	v_cvt_pk_bf16_f32 v83, v84, v85
	v_cvt_pk_bf16_f32 v84, v86, v87
	v_cvt_pk_bf16_f32 v85, v88, v89
	ds_read_b64_tr_b16 v[86:87], v157 offset:32768
	ds_read_b64_tr_b16 v[88:89], v157 offset:33280
	s_waitcnt lgkmcnt(0)
	v_mfma_f32_32x32x16_bf16 v[48:63], v[86:89], v[82:85], v[48:63]
	ds_read_b64_tr_b16 v[86:87], v157 offset:36864
	ds_read_b64_tr_b16 v[88:89], v157 offset:37376
	v_exp_f32_e32 v90, v90
	v_exp_f32_e32 v91, v91
	v_exp_f32_e32 v92, v92
	v_exp_f32_e32 v93, v93
	v_exp_f32_e32 v94, v94
	v_exp_f32_e32 v95, v95
	s_waitcnt lgkmcnt(0)
	v_mfma_f32_32x32x16_bf16 v[32:47], v[86:89], v[82:85], v[32:47]
	ds_read_b64_tr_b16 v[86:87], v157 offset:40960
	ds_read_b64_tr_b16 v[88:89], v157 offset:41472
	v_exp_f32_e32 v96, v96
	v_exp_f32_e32 v97, v97
	v_add_f32_e32 v145, v90, v145
	v_add_f32_e32 v145, v91, v145
	v_add_f32_e32 v145, v92, v145
	v_add_f32_e32 v145, v93, v145
	s_waitcnt lgkmcnt(0)
	v_mfma_f32_32x32x16_bf16 v[16:31], v[86:89], v[82:85], v[16:31]
	ds_read_b64_tr_b16 v[86:87], v157 offset:45056
	ds_read_b64_tr_b16 v[88:89], v157 offset:45568
	v_add_f32_e32 v145, v94, v145
	v_add_f32_e32 v145, v95, v145
	v_add_f32_e32 v145, v96, v145
	v_add_f32_e32 v145, v97, v145
	v_add_f32_e32 v144, v144, v145
	s_waitcnt lgkmcnt(0)
	v_mfma_f32_32x32x16_bf16 v[0:15], v[86:89], v[82:85], v[0:15]
	ds_read_b64_tr_b16 v[86:87], v157 offset:33792
	ds_read_b64_tr_b16 v[88:89], v157 offset:34304
	v_cvt_pk_bf16_f32 v82, v90, v91
	v_cvt_pk_bf16_f32 v83, v92, v93
	v_cvt_pk_bf16_f32 v84, v94, v95
	v_cvt_pk_bf16_f32 v85, v96, v97
	s_waitcnt lgkmcnt(0)
	s_nop 0
	v_mfma_f32_32x32x16_bf16 v[48:63], v[86:89], v[82:85], v[48:63]
	ds_read_b64_tr_b16 v[86:87], v157 offset:37888
	ds_read_b64_tr_b16 v[88:89], v157 offset:38400
	s_waitcnt lgkmcnt(0)
	v_mfma_f32_32x32x16_bf16 v[32:47], v[86:89], v[82:85], v[32:47]
	ds_read_b64_tr_b16 v[86:87], v157 offset:41984
	ds_read_b64_tr_b16 v[88:89], v157 offset:42496
	s_waitcnt lgkmcnt(0)
	v_mfma_f32_32x32x16_bf16 v[16:31], v[86:89], v[82:85], v[16:31]
	ds_read_b64_tr_b16 v[86:87], v157 offset:46080
	ds_read_b64_tr_b16 v[88:89], v157 offset:46592
	ds_read_b128 v[206:209], v165 offset:24576
	s_waitcnt lgkmcnt(1)
	v_mfma_f32_32x32x16_bf16 v[0:15], v[86:89], v[82:85], v[0:15]
	ds_read_b128 v[170:173], v162 offset:24576
	s_waitcnt lgkmcnt(0)
	v_mfma_f32_32x32x16_bf16 v[82:97], v[170:173], v[98:101], v[66:81]
	ds_read_b128 v[170:173], v163 offset:24576
	s_waitcnt lgkmcnt(0)
	v_mfma_f32_32x32x16_bf16 v[82:97], v[170:173], v[102:105], v[82:97]
	ds_read_b128 v[170:173], v164 offset:24576
	s_waitcnt lgkmcnt(0)
	v_mfma_f32_32x32x16_bf16 v[82:97], v[170:173], v[106:109], v[82:97]
	v_mfma_f32_32x32x16_bf16 v[82:97], v[206:209], v[110:113], v[82:97]
	s_nop 11
	v_maximum3_f32 v148, v82, v83, v83
	v_maximum3_f32 v148, v148, v84, v85
	v_maximum3_f32 v148, v148, v86, v87
	v_maximum3_f32 v148, v148, v88, v89
	v_maximum3_f32 v148, v148, v90, v91
	v_maximum3_f32 v148, v148, v92, v93
	v_maximum3_f32 v148, v148, v94, v95
	v_maximum3_f32 v148, v148, v96, v97
	v_mov_b32_e32 v167, v148
	s_nop 1
	v_permlane32_swap_b32_e32 v148, v167
	v_maximum3_f32 v148, v148, v167, v167
	v_cmp_lt_f32_e32 vcc, s80, v148
	s_cbranch_vccz .LBB0_391
	v_max_f32_e32 v148, v148, v148
	v_max_f32_e32 v68, 0, v148
	v_exp_f32_e64 v70, -v68
	v_add_f32_e32 v166, v166, v68
	v_xor_b32_e32 v66, 0x80000000, v166
	v_pk_add_f32 v[82:83], v[82:83], v[68:69] op_sel_hi:[1,0] neg_lo:[0,1] neg_hi:[0,1]
	v_mul_f32_e32 v144, v144, v70
	v_pk_add_f32 v[84:85], v[84:85], v[68:69] op_sel_hi:[1,0] neg_lo:[0,1] neg_hi:[0,1]
	v_pk_add_f32 v[86:87], v[86:87], v[68:69] op_sel_hi:[1,0] neg_lo:[0,1] neg_hi:[0,1]
	v_pk_add_f32 v[88:89], v[88:89], v[68:69] op_sel_hi:[1,0] neg_lo:[0,1] neg_hi:[0,1]
	v_pk_add_f32 v[90:91], v[90:91], v[68:69] op_sel_hi:[1,0] neg_lo:[0,1] neg_hi:[0,1]
	v_pk_add_f32 v[92:93], v[92:93], v[68:69] op_sel_hi:[1,0] neg_lo:[0,1] neg_hi:[0,1]
	v_pk_add_f32 v[94:95], v[94:95], v[68:69] op_sel_hi:[1,0] neg_lo:[0,1] neg_hi:[0,1]
	v_pk_add_f32 v[96:97], v[96:97], v[68:69] op_sel_hi:[1,0] neg_lo:[0,1] neg_hi:[0,1]
	v_pk_mul_f32 v[62:63], v[62:63], v[70:71] op_sel_hi:[1,0]
	v_pk_mul_f32 v[60:61], v[60:61], v[70:71] op_sel_hi:[1,0]
	v_pk_mul_f32 v[58:59], v[58:59], v[70:71] op_sel_hi:[1,0]
	v_pk_mul_f32 v[56:57], v[56:57], v[70:71] op_sel_hi:[1,0]
	v_pk_mul_f32 v[54:55], v[54:55], v[70:71] op_sel_hi:[1,0]
	v_pk_mul_f32 v[52:53], v[52:53], v[70:71] op_sel_hi:[1,0]
	v_pk_mul_f32 v[50:51], v[50:51], v[70:71] op_sel_hi:[1,0]
	v_pk_mul_f32 v[48:49], v[48:49], v[70:71] op_sel_hi:[1,0]
	v_pk_mul_f32 v[46:47], v[46:47], v[70:71] op_sel_hi:[1,0]
	v_pk_mul_f32 v[44:45], v[44:45], v[70:71] op_sel_hi:[1,0]
	v_pk_mul_f32 v[42:43], v[42:43], v[70:71] op_sel_hi:[1,0]
	v_pk_mul_f32 v[40:41], v[40:41], v[70:71] op_sel_hi:[1,0]
	v_pk_mul_f32 v[38:39], v[38:39], v[70:71] op_sel_hi:[1,0]
	v_pk_mul_f32 v[36:37], v[36:37], v[70:71] op_sel_hi:[1,0]
	v_pk_mul_f32 v[34:35], v[34:35], v[70:71] op_sel_hi:[1,0]
	v_pk_mul_f32 v[32:33], v[32:33], v[70:71] op_sel_hi:[1,0]
	v_pk_mul_f32 v[30:31], v[30:31], v[70:71] op_sel_hi:[1,0]
	v_pk_mul_f32 v[28:29], v[28:29], v[70:71] op_sel_hi:[1,0]
	v_pk_mul_f32 v[26:27], v[26:27], v[70:71] op_sel_hi:[1,0]
	v_pk_mul_f32 v[24:25], v[24:25], v[70:71] op_sel_hi:[1,0]
	v_pk_mul_f32 v[22:23], v[22:23], v[70:71] op_sel_hi:[1,0]
	v_pk_mul_f32 v[20:21], v[20:21], v[70:71] op_sel_hi:[1,0]
	v_pk_mul_f32 v[18:19], v[18:19], v[70:71] op_sel_hi:[1,0]
	v_pk_mul_f32 v[16:17], v[16:17], v[70:71] op_sel_hi:[1,0]
	v_pk_mul_f32 v[14:15], v[14:15], v[70:71] op_sel_hi:[1,0]
	v_pk_mul_f32 v[12:13], v[12:13], v[70:71] op_sel_hi:[1,0]
	v_pk_mul_f32 v[10:11], v[10:11], v[70:71] op_sel_hi:[1,0]
	v_pk_mul_f32 v[8:9], v[8:9], v[70:71] op_sel_hi:[1,0]
	v_pk_mul_f32 v[6:7], v[6:7], v[70:71] op_sel_hi:[1,0]
	v_pk_mul_f32 v[4:5], v[4:5], v[70:71] op_sel_hi:[1,0]
	v_pk_mul_f32 v[2:3], v[2:3], v[70:71] op_sel_hi:[1,0]
	v_pk_mul_f32 v[0:1], v[0:1], v[70:71] op_sel_hi:[1,0]
	v_mov_b32_e32 v67, v66
	v_mov_b32_e32 v68, v66
	v_mov_b32_e32 v69, v66
	v_mov_b32_e32 v70, v66
	v_mov_b32_e32 v71, v66
	v_mov_b32_e32 v72, v66
	v_mov_b32_e32 v73, v66
	v_mov_b32_e32 v74, v66
	v_mov_b32_e32 v75, v66
	v_mov_b32_e32 v76, v66
	v_mov_b32_e32 v77, v66
	v_mov_b32_e32 v78, v66
	v_mov_b32_e32 v79, v66
	v_mov_b32_e32 v80, v66
	v_mov_b32_e32 v81, v66
	s_branch .LBB0_392
